# scaled-state scan: decay folded into 8-token group prefix (producer), consumer drops w read + 2 VALU per step
# speedup vs baseline: 1.0055x; 1.0055x over previous
; #define LAS __attribute__((address_space(3)))
; template <int CTRL> __device__ __forceinline__ float dpp_f(float x) { return __int_as_float(__builtin_amdgcn_update_dpp(0, __float_as_int(x), CTRL, 0xf, 0xf, false)); }
; __device__ __forceinline__ void p8_scan(const Args& a, LAS unsigned char* lds) {
;     ...
;             for (int c = 0; c < T / TC; ++c) {
;                 const int cur = c & 1;
;                 const LAS float* bt = buf + cur * TC * SPITCH;
;                 LAS float* yd = holds_y ? (ybuf + cur * TC * 64 + 4 * (4 * w + (lane >> 4)) + ((lane & 15) >> 2)) : (dump + lane);
;                 ScanOps o; scan_ld(o, bt, jq4, myrow);
; #pragma unroll 16
;                 for (int tt = 0; tt < TC; ++tt) {
;                     ScanOps n; scan_ld(n, bt + (tt + 1 < TC ? tt + 1 : tt) * SPITCH, jq4, myrow);
;                     __builtin_amdgcn_sched_barrier(0);
;                     f32x2 ta = S01 * o.al.lo, ty = S01 * o.wr.lo; ta = S23 * o.al.hi + ta; ty = S23 * o.wr.hi + ty;
;                     float pa = ta.x + ta.y, py = ty.x + ty.y;
;                     f32x2 kv01 = o.kv.lo * o.vi, kv23 = o.kv.hi * o.vi;
;     ...
;                     asm volatile("" : "+v"(kv01), "+v"(kv23), "+v"(vc));
;                     pa += dpp_f<0x121>(pa); py += dpp_f<0x121>(py); pa += dpp_f<0x122>(pa); py += dpp_f<0x122>(py);
;                     pa += dpp_f<0x124>(pa); pa += dpp_f<0x128>(pa);
;                     S01 = S01 * o.wv.lo + (o.be.lo * pa + kv01);
;                     S23 = S23 * o.wv.hi + (o.be.hi * pa + kv23);
;     ...
;                     __builtin_amdgcn_sched_barrier(0);
;                     o = n;
;                 }
;                 __syncthreads();
.LBB0_1090:
	s_and_b32 s43, s14, 1
	s_mul_i32 s52, s43, 0xc400
	s_lshl_b32 s43, s43, 13
	v_lshl_add_u32 v38, v27, 2, s52
	v_lshl_add_u32 v39, v1, 2, s52
	v_add_u32_e32 v41, s43, v123
	v_cndmask_b32_e64 v41, v124, v41, s[2:3]
	ds_read_b128 v[10:13], v38 offset:512
	ds_read_b128 v[6:9], v38 offset:256
	ds_read_b32 v28, v39 offset:1280
	ds_read_b128 v[14:17], v38 offset:768
	ds_read_b128 v[18:21], v38 offset:1024
	s_waitcnt lgkmcnt(2)
	v_pk_mul_f32 v[34:35], v[22:23], v[10:11]
	v_pk_fma_f32 v[34:35], v[24:25], v[12:13], v[34:35]
	ds_read_b128 v[50:53], v38 offset:2080
	ds_read_b128 v[46:49], v38 offset:1824
	ds_read_b32 v62, v39 offset:2848
	ds_read_b128 v[54:57], v38 offset:2336
	ds_read_b128 v[58:61], v38 offset:2592
	v_add_f32_e32 v34, v34, v35
	v_pk_fma_f32 v[22:23], v[6:7], v[28:29], v[22:23] op_sel_hi:[1,0,1]
	v_pk_fma_f32 v[24:25], v[8:9], v[28:29], v[24:25] op_sel_hi:[1,0,1]
	v_add_f32_dpp v34, v34, v34 row_ror:1 row_mask:0xf bank_mask:0xf bound_ctrl:1
	s_nop 0
	s_nop 0
	v_add_f32_dpp v34, v34, v34 row_ror:2 row_mask:0xf bank_mask:0xf bound_ctrl:1
	s_nop 0
	s_nop 0
	v_add_f32_dpp v34, v34, v34 row_ror:4 row_mask:0xf bank_mask:0xf bound_ctrl:1
	s_waitcnt lgkmcnt(6)
	s_nop 0
	s_nop 0
	v_add_f32_dpp v34, v34, v34 row_ror:8 row_mask:0xf bank_mask:0xf bound_ctrl:1
	v_pk_fma_f32 v[22:23], v[14:15], v[34:35], v[22:23] op_sel_hi:[1,0,1]
	v_pk_fma_f32 v[24:25], v[16:17], v[34:35], v[24:25] op_sel_hi:[1,0,1]
	s_waitcnt lgkmcnt(2)
	v_pk_mul_f32 v[34:35], v[22:23], v[50:51]
	v_pk_mul_f32 v[36:37], v[22:23], v[18:19]
	v_pk_fma_f32 v[34:35], v[24:25], v[52:53], v[34:35]
	v_pk_fma_f32 v[36:37], v[24:25], v[20:21], v[36:37]
	ds_read_b128 v[10:13], v38 offset:3648
	ds_read_b128 v[6:9], v38 offset:3392
	ds_read_b32 v28, v39 offset:4416
	ds_read_b128 v[14:17], v38 offset:3904
	ds_read_b128 v[18:21], v38 offset:4160
	v_add_f32_e32 v34, v34, v35
	v_add_f32_e32 v36, v36, v37
	v_pk_fma_f32 v[22:23], v[46:47], v[62:63], v[22:23] op_sel_hi:[1,0,1]
	v_add_f32_dpp v34, v34, v34 row_ror:1 row_mask:0xf bank_mask:0xf bound_ctrl:1
	v_add_f32_dpp v36, v36, v36 row_ror:1 row_mask:0xf bank_mask:0xf bound_ctrl:1
	v_pk_fma_f32 v[24:25], v[48:49], v[62:63], v[24:25] op_sel_hi:[1,0,1]
	v_add_f32_dpp v34, v34, v34 row_ror:2 row_mask:0xf bank_mask:0xf bound_ctrl:1
	v_add_f32_dpp v36, v36, v36 row_ror:2 row_mask:0xf bank_mask:0xf bound_ctrl:1
	s_nop 0
	v_add_f32_dpp v34, v34, v34 row_ror:4 row_mask:0xf bank_mask:0xf bound_ctrl:1
	s_waitcnt lgkmcnt(6)
	s_nop 0
	s_nop 0
	v_add_f32_dpp v34, v34, v34 row_ror:8 row_mask:0xf bank_mask:0xf bound_ctrl:1
	v_pk_fma_f32 v[22:23], v[54:55], v[34:35], v[22:23] op_sel_hi:[1,0,1]
	v_pk_fma_f32 v[24:25], v[56:57], v[34:35], v[24:25] op_sel_hi:[1,0,1]
	s_waitcnt lgkmcnt(2)
	v_pk_mul_f32 v[34:35], v[22:23], v[10:11]
	v_pk_mul_f32 v[66:67], v[22:23], v[58:59]
	v_pk_fma_f32 v[34:35], v[24:25], v[12:13], v[34:35]
	v_pk_fma_f32 v[66:67], v[24:25], v[60:61], v[66:67]
	ds_read_b128 v[50:53], v38 offset:5216
	ds_read_b128 v[46:49], v38 offset:4960
	ds_read_b32 v62, v39 offset:5984
	ds_read_b128 v[54:57], v38 offset:5472
	ds_read_b128 v[58:61], v38 offset:5728
	v_add_f32_e32 v34, v34, v35
	v_add_f32_e32 v66, v66, v67
	v_pk_fma_f32 v[22:23], v[6:7], v[28:29], v[22:23] op_sel_hi:[1,0,1]
	v_add_f32_dpp v34, v34, v34 row_ror:1 row_mask:0xf bank_mask:0xf bound_ctrl:1
	v_add_f32_dpp v66, v66, v66 row_ror:1 row_mask:0xf bank_mask:0xf bound_ctrl:1
	v_pk_fma_f32 v[24:25], v[8:9], v[28:29], v[24:25] op_sel_hi:[1,0,1]
	v_add_f32_dpp v34, v34, v34 row_ror:2 row_mask:0xf bank_mask:0xf bound_ctrl:1
	v_add_f32_dpp v66, v66, v66 row_ror:2 row_mask:0xf bank_mask:0xf bound_ctrl:1
	ds_write2st64_b32 v41, v36, v66 offset0:0 offset1:1
	v_add_f32_dpp v34, v34, v34 row_ror:4 row_mask:0xf bank_mask:0xf bound_ctrl:1
	s_waitcnt lgkmcnt(7)
	s_nop 0
	s_nop 0
	v_add_f32_dpp v34, v34, v34 row_ror:8 row_mask:0xf bank_mask:0xf bound_ctrl:1
	v_pk_fma_f32 v[22:23], v[14:15], v[34:35], v[22:23] op_sel_hi:[1,0,1]
	v_pk_fma_f32 v[24:25], v[16:17], v[34:35], v[24:25] op_sel_hi:[1,0,1]
	s_waitcnt lgkmcnt(3)
	v_pk_mul_f32 v[34:35], v[22:23], v[50:51]
	v_pk_mul_f32 v[36:37], v[22:23], v[18:19]
	v_pk_fma_f32 v[34:35], v[24:25], v[52:53], v[34:35]
	v_pk_fma_f32 v[36:37], v[24:25], v[20:21], v[36:37]
	ds_read_b128 v[10:13], v38 offset:6784
	ds_read_b128 v[6:9], v38 offset:6528
	ds_read_b32 v28, v39 offset:7552
	ds_read_b128 v[14:17], v38 offset:7040
	ds_read_b128 v[18:21], v38 offset:7296
	v_add_f32_e32 v34, v34, v35
	v_add_f32_e32 v36, v36, v37
	v_pk_fma_f32 v[22:23], v[46:47], v[62:63], v[22:23] op_sel_hi:[1,0,1]
	v_add_f32_dpp v34, v34, v34 row_ror:1 row_mask:0xf bank_mask:0xf bound_ctrl:1
	v_add_f32_dpp v36, v36, v36 row_ror:1 row_mask:0xf bank_mask:0xf bound_ctrl:1
	v_pk_fma_f32 v[24:25], v[48:49], v[62:63], v[24:25] op_sel_hi:[1,0,1]
	v_add_f32_dpp v34, v34, v34 row_ror:2 row_mask:0xf bank_mask:0xf bound_ctrl:1
	v_add_f32_dpp v36, v36, v36 row_ror:2 row_mask:0xf bank_mask:0xf bound_ctrl:1
	s_nop 0
	v_add_f32_dpp v34, v34, v34 row_ror:4 row_mask:0xf bank_mask:0xf bound_ctrl:1
	s_waitcnt lgkmcnt(7)
	s_nop 0
	s_nop 0
	v_add_f32_dpp v34, v34, v34 row_ror:8 row_mask:0xf bank_mask:0xf bound_ctrl:1
	v_pk_fma_f32 v[22:23], v[54:55], v[34:35], v[22:23] op_sel_hi:[1,0,1]
	v_pk_fma_f32 v[24:25], v[56:57], v[34:35], v[24:25] op_sel_hi:[1,0,1]
	s_waitcnt lgkmcnt(2)
; #define LAS __attribute__((address_space(3)))
; template <int CTRL> __device__ __forceinline__ float dpp_f(float x) { return __int_as_float(__builtin_amdgcn_update_dpp(0, __float_as_int(x), CTRL, 0xf, 0xf, false)); }
; __device__ __forceinline__ void p8_scan(const Args& a, LAS unsigned char* lds) {
;     ...
;             for (int c = 0; c < T / TC; ++c) {
;                 const int cur = c & 1;
;                 const LAS float* bt = buf + cur * TC * SPITCH;
;                 LAS float* yd = holds_y ? (ybuf + cur * TC * 64 + 4 * (4 * w + (lane >> 4)) + ((lane & 15) >> 2)) : (dump + lane);
;                 ScanOps o; scan_ld(o, bt, jq4, myrow);
; #pragma unroll 16
;                 for (int tt = 0; tt < TC; ++tt) {
;                     ScanOps n; scan_ld(n, bt + (tt + 1 < TC ? tt + 1 : tt) * SPITCH, jq4, myrow);
;                     __builtin_amdgcn_sched_barrier(0);
;                     f32x2 ta = S01 * o.al.lo, ty = S01 * o.wr.lo; ta = S23 * o.al.hi + ta; ty = S23 * o.wr.hi + ty;
;                     float pa = ta.x + ta.y, py = ty.x + ty.y;
;                     f32x2 kv01 = o.kv.lo * o.vi, kv23 = o.kv.hi * o.vi;
;     ...
;                     asm volatile("" : "+v"(kv01), "+v"(kv23), "+v"(vc));
;                     pa += dpp_f<0x121>(pa); py += dpp_f<0x121>(py); pa += dpp_f<0x122>(pa); py += dpp_f<0x122>(py);
;                     pa += dpp_f<0x124>(pa); pa += dpp_f<0x128>(pa);
;                     S01 = S01 * o.wv.lo + (o.be.lo * pa + kv01);
;                     S23 = S23 * o.wv.hi + (o.be.hi * pa + kv23);
;     ...
;                     __builtin_amdgcn_sched_barrier(0);
;                     o = n;
;                 }
;                 __syncthreads();
	v_pk_mul_f32 v[34:35], v[22:23], v[10:11]
	v_pk_mul_f32 v[66:67], v[22:23], v[58:59]
	v_pk_fma_f32 v[34:35], v[24:25], v[12:13], v[34:35]
	v_pk_fma_f32 v[66:67], v[24:25], v[60:61], v[66:67]
	ds_read_b128 v[50:53], v38 offset:8352
	ds_read_b128 v[46:49], v38 offset:8096
	ds_read_b32 v62, v39 offset:9120
	ds_read_b128 v[54:57], v38 offset:8608
	ds_read_b128 v[58:61], v38 offset:8864
	v_add_f32_e32 v34, v34, v35
	v_add_f32_e32 v66, v66, v67
	v_pk_fma_f32 v[22:23], v[6:7], v[28:29], v[22:23] op_sel_hi:[1,0,1]
	v_add_f32_dpp v34, v34, v34 row_ror:1 row_mask:0xf bank_mask:0xf bound_ctrl:1
	v_add_f32_dpp v66, v66, v66 row_ror:1 row_mask:0xf bank_mask:0xf bound_ctrl:1
	v_pk_fma_f32 v[24:25], v[8:9], v[28:29], v[24:25] op_sel_hi:[1,0,1]
	v_add_f32_dpp v34, v34, v34 row_ror:2 row_mask:0xf bank_mask:0xf bound_ctrl:1
	v_add_f32_dpp v66, v66, v66 row_ror:2 row_mask:0xf bank_mask:0xf bound_ctrl:1
	ds_write2st64_b32 v41, v36, v66 offset0:2 offset1:3
	v_add_f32_dpp v34, v34, v34 row_ror:4 row_mask:0xf bank_mask:0xf bound_ctrl:1
	s_waitcnt lgkmcnt(7)
	s_nop 0
	s_nop 0
	v_add_f32_dpp v34, v34, v34 row_ror:8 row_mask:0xf bank_mask:0xf bound_ctrl:1
	v_pk_fma_f32 v[22:23], v[14:15], v[34:35], v[22:23] op_sel_hi:[1,0,1]
	v_pk_fma_f32 v[24:25], v[16:17], v[34:35], v[24:25] op_sel_hi:[1,0,1]
	s_waitcnt lgkmcnt(3)
	v_pk_mul_f32 v[34:35], v[22:23], v[50:51]
	v_pk_mul_f32 v[36:37], v[22:23], v[18:19]
	v_pk_fma_f32 v[34:35], v[24:25], v[52:53], v[34:35]
	v_pk_fma_f32 v[36:37], v[24:25], v[20:21], v[36:37]
	ds_read_b128 v[10:13], v38 offset:9920
	ds_read_b128 v[6:9], v38 offset:9664
	ds_read_b32 v28, v39 offset:10688
	ds_read_b128 v[14:17], v38 offset:10176
	ds_read_b128 v[18:21], v38 offset:10432
	v_add_f32_e32 v34, v34, v35
	v_add_f32_e32 v36, v36, v37
	v_pk_fma_f32 v[22:23], v[46:47], v[62:63], v[22:23] op_sel_hi:[1,0,1]
	v_add_f32_dpp v34, v34, v34 row_ror:1 row_mask:0xf bank_mask:0xf bound_ctrl:1
	v_add_f32_dpp v36, v36, v36 row_ror:1 row_mask:0xf bank_mask:0xf bound_ctrl:1
	v_pk_fma_f32 v[24:25], v[48:49], v[62:63], v[24:25] op_sel_hi:[1,0,1]
	v_add_f32_dpp v34, v34, v34 row_ror:2 row_mask:0xf bank_mask:0xf bound_ctrl:1
	v_add_f32_dpp v36, v36, v36 row_ror:2 row_mask:0xf bank_mask:0xf bound_ctrl:1
	s_nop 0
	v_add_f32_dpp v34, v34, v34 row_ror:4 row_mask:0xf bank_mask:0xf bound_ctrl:1
	s_waitcnt lgkmcnt(7)
	s_nop 0
	s_nop 0
	v_add_f32_dpp v34, v34, v34 row_ror:8 row_mask:0xf bank_mask:0xf bound_ctrl:1
	v_pk_fma_f32 v[22:23], v[54:55], v[34:35], v[22:23] op_sel_hi:[1,0,1]
	v_pk_fma_f32 v[24:25], v[56:57], v[34:35], v[24:25] op_sel_hi:[1,0,1]
	s_waitcnt lgkmcnt(2)
	v_pk_mul_f32 v[34:35], v[22:23], v[10:11]
	v_pk_mul_f32 v[66:67], v[22:23], v[58:59]
	v_pk_fma_f32 v[34:35], v[24:25], v[12:13], v[34:35]
	v_pk_fma_f32 v[66:67], v[24:25], v[60:61], v[66:67]
	ds_read_b128 v[50:53], v38 offset:11488
	ds_read_b128 v[46:49], v38 offset:11232
	ds_read_b32 v62, v39 offset:12256
	ds_read_b128 v[42:45], v38 offset:10976
	ds_read_b128 v[54:57], v38 offset:11744
	ds_read_b128 v[58:61], v38 offset:12000
	v_add_f32_e32 v34, v34, v35
	v_add_f32_e32 v66, v66, v67
	v_pk_fma_f32 v[22:23], v[6:7], v[28:29], v[22:23] op_sel_hi:[1,0,1]
	v_add_f32_dpp v34, v34, v34 row_ror:1 row_mask:0xf bank_mask:0xf bound_ctrl:1
	v_add_f32_dpp v66, v66, v66 row_ror:1 row_mask:0xf bank_mask:0xf bound_ctrl:1
	v_pk_fma_f32 v[24:25], v[8:9], v[28:29], v[24:25] op_sel_hi:[1,0,1]
	v_add_f32_dpp v34, v34, v34 row_ror:2 row_mask:0xf bank_mask:0xf bound_ctrl:1
	v_add_f32_dpp v66, v66, v66 row_ror:2 row_mask:0xf bank_mask:0xf bound_ctrl:1
	ds_write2st64_b32 v41, v36, v66 offset0:4 offset1:5
	v_add_f32_dpp v34, v34, v34 row_ror:4 row_mask:0xf bank_mask:0xf bound_ctrl:1
	s_waitcnt lgkmcnt(8)
	s_nop 0
	s_nop 0
	v_add_f32_dpp v34, v34, v34 row_ror:8 row_mask:0xf bank_mask:0xf bound_ctrl:1
	v_pk_fma_f32 v[22:23], v[14:15], v[34:35], v[22:23] op_sel_hi:[1,0,1]
	v_pk_fma_f32 v[24:25], v[16:17], v[34:35], v[24:25] op_sel_hi:[1,0,1]
	s_waitcnt lgkmcnt(4)
	v_pk_mul_f32 v[34:35], v[22:23], v[50:51]
	v_pk_mul_f32 v[36:37], v[22:23], v[18:19]
	v_pk_fma_f32 v[34:35], v[24:25], v[52:53], v[34:35]
	v_pk_fma_f32 v[36:37], v[24:25], v[20:21], v[36:37]
	ds_read_b128 v[10:13], v38 offset:13056
	ds_read_b128 v[6:9], v38 offset:12800
	ds_read_b32 v28, v39 offset:13824
	ds_read_b128 v[14:17], v38 offset:13312
	ds_read_b128 v[18:21], v38 offset:13568
	v_add_f32_e32 v34, v34, v35
	v_add_f32_e32 v36, v36, v37
	v_pk_fma_f32 v[22:23], v[46:47], v[62:63], v[22:23] op_sel_hi:[1,0,1]
	v_add_f32_dpp v34, v34, v34 row_ror:1 row_mask:0xf bank_mask:0xf bound_ctrl:1
	v_add_f32_dpp v36, v36, v36 row_ror:1 row_mask:0xf bank_mask:0xf bound_ctrl:1
	v_pk_fma_f32 v[24:25], v[48:49], v[62:63], v[24:25] op_sel_hi:[1,0,1]
	v_add_f32_dpp v34, v34, v34 row_ror:2 row_mask:0xf bank_mask:0xf bound_ctrl:1
	v_add_f32_dpp v36, v36, v36 row_ror:2 row_mask:0xf bank_mask:0xf bound_ctrl:1
	s_nop 0
	v_add_f32_dpp v34, v34, v34 row_ror:4 row_mask:0xf bank_mask:0xf bound_ctrl:1
	s_waitcnt lgkmcnt(7)
	s_nop 0
	s_nop 0
	v_add_f32_dpp v34, v34, v34 row_ror:8 row_mask:0xf bank_mask:0xf bound_ctrl:1
	v_pk_fma_f32 v[22:23], v[54:55], v[34:35], v[22:23] op_sel_hi:[1,0,1]
	v_pk_fma_f32 v[24:25], v[56:57], v[34:35], v[24:25] op_sel_hi:[1,0,1]
	s_waitcnt lgkmcnt(2)
; #define LAS __attribute__((address_space(3)))
; template <int CTRL> __device__ __forceinline__ float dpp_f(float x) { return __int_as_float(__builtin_amdgcn_update_dpp(0, __float_as_int(x), CTRL, 0xf, 0xf, false)); }
; __device__ __forceinline__ void p8_scan(const Args& a, LAS unsigned char* lds) {
;     ...
;             for (int c = 0; c < T / TC; ++c) {
;                 const int cur = c & 1;
;                 const LAS float* bt = buf + cur * TC * SPITCH;
;                 LAS float* yd = holds_y ? (ybuf + cur * TC * 64 + 4 * (4 * w + (lane >> 4)) + ((lane & 15) >> 2)) : (dump + lane);
;                 ScanOps o; scan_ld(o, bt, jq4, myrow);
; #pragma unroll 16
;                 for (int tt = 0; tt < TC; ++tt) {
;                     ScanOps n; scan_ld(n, bt + (tt + 1 < TC ? tt + 1 : tt) * SPITCH, jq4, myrow);
;                     __builtin_amdgcn_sched_barrier(0);
;                     f32x2 ta = S01 * o.al.lo, ty = S01 * o.wr.lo; ta = S23 * o.al.hi + ta; ty = S23 * o.wr.hi + ty;
;                     float pa = ta.x + ta.y, py = ty.x + ty.y;
;                     f32x2 kv01 = o.kv.lo * o.vi, kv23 = o.kv.hi * o.vi;
;     ...
;                     asm volatile("" : "+v"(kv01), "+v"(kv23), "+v"(vc));
;                     pa += dpp_f<0x121>(pa); py += dpp_f<0x121>(py); pa += dpp_f<0x122>(pa); py += dpp_f<0x122>(py);
;                     pa += dpp_f<0x124>(pa); pa += dpp_f<0x128>(pa);
;                     S01 = S01 * o.wv.lo + (o.be.lo * pa + kv01);
;                     S23 = S23 * o.wv.hi + (o.be.hi * pa + kv23);
;     ...
;                     __builtin_amdgcn_sched_barrier(0);
;                     o = n;
;                 }
;                 __syncthreads();
	v_pk_mul_f32 v[66:67], v[22:23], v[58:59]
	v_pk_fma_f32 v[66:67], v[24:25], v[60:61], v[66:67]
	v_pk_mul_f32 v[22:23], v[22:23], v[42:43]
	v_pk_mul_f32 v[24:25], v[24:25], v[44:45]
	v_pk_mul_f32 v[34:35], v[22:23], v[10:11]
	v_pk_fma_f32 v[34:35], v[24:25], v[12:13], v[34:35]
	ds_read_b128 v[50:53], v38 offset:14624
	ds_read_b128 v[46:49], v38 offset:14368
	ds_read_b32 v62, v39 offset:15392
	ds_read_b128 v[54:57], v38 offset:14880
	ds_read_b128 v[58:61], v38 offset:15136
	v_add_f32_e32 v34, v34, v35
	v_add_f32_e32 v66, v66, v67
	v_pk_fma_f32 v[22:23], v[6:7], v[28:29], v[22:23] op_sel_hi:[1,0,1]
	v_add_f32_dpp v34, v34, v34 row_ror:1 row_mask:0xf bank_mask:0xf bound_ctrl:1
	v_add_f32_dpp v66, v66, v66 row_ror:1 row_mask:0xf bank_mask:0xf bound_ctrl:1
	v_pk_fma_f32 v[24:25], v[8:9], v[28:29], v[24:25] op_sel_hi:[1,0,1]
	v_add_f32_dpp v34, v34, v34 row_ror:2 row_mask:0xf bank_mask:0xf bound_ctrl:1
	v_add_f32_dpp v66, v66, v66 row_ror:2 row_mask:0xf bank_mask:0xf bound_ctrl:1
	ds_write2st64_b32 v41, v36, v66 offset0:6 offset1:7
	v_add_f32_dpp v34, v34, v34 row_ror:4 row_mask:0xf bank_mask:0xf bound_ctrl:1
	s_waitcnt lgkmcnt(7)
	s_nop 0
	s_nop 0
	v_add_f32_dpp v34, v34, v34 row_ror:8 row_mask:0xf bank_mask:0xf bound_ctrl:1
	v_pk_fma_f32 v[22:23], v[14:15], v[34:35], v[22:23] op_sel_hi:[1,0,1]
	v_pk_fma_f32 v[24:25], v[16:17], v[34:35], v[24:25] op_sel_hi:[1,0,1]
	s_waitcnt lgkmcnt(3)
	v_pk_mul_f32 v[34:35], v[22:23], v[50:51]
	v_pk_mul_f32 v[36:37], v[22:23], v[18:19]
	v_pk_fma_f32 v[34:35], v[24:25], v[52:53], v[34:35]
	v_pk_fma_f32 v[36:37], v[24:25], v[20:21], v[36:37]
	ds_read_b128 v[10:13], v38 offset:16192
	ds_read_b128 v[6:9], v38 offset:15936
	ds_read_b32 v28, v39 offset:16960
	ds_read_b128 v[14:17], v38 offset:16448
	ds_read_b128 v[18:21], v38 offset:16704
	v_add_f32_e32 v34, v34, v35
	v_add_f32_e32 v36, v36, v37
	v_pk_fma_f32 v[22:23], v[46:47], v[62:63], v[22:23] op_sel_hi:[1,0,1]
	v_add_f32_dpp v34, v34, v34 row_ror:1 row_mask:0xf bank_mask:0xf bound_ctrl:1
	v_add_f32_dpp v36, v36, v36 row_ror:1 row_mask:0xf bank_mask:0xf bound_ctrl:1
	v_pk_fma_f32 v[24:25], v[48:49], v[62:63], v[24:25] op_sel_hi:[1,0,1]
	v_add_f32_dpp v34, v34, v34 row_ror:2 row_mask:0xf bank_mask:0xf bound_ctrl:1
	v_add_f32_dpp v36, v36, v36 row_ror:2 row_mask:0xf bank_mask:0xf bound_ctrl:1
	s_nop 0
	v_add_f32_dpp v34, v34, v34 row_ror:4 row_mask:0xf bank_mask:0xf bound_ctrl:1
	s_waitcnt lgkmcnt(7)
	s_nop 0
	s_nop 0
	v_add_f32_dpp v34, v34, v34 row_ror:8 row_mask:0xf bank_mask:0xf bound_ctrl:1
	v_pk_fma_f32 v[22:23], v[54:55], v[34:35], v[22:23] op_sel_hi:[1,0,1]
	v_pk_fma_f32 v[24:25], v[56:57], v[34:35], v[24:25] op_sel_hi:[1,0,1]
	s_waitcnt lgkmcnt(2)
	v_pk_mul_f32 v[34:35], v[22:23], v[10:11]
	v_pk_mul_f32 v[66:67], v[22:23], v[58:59]
	v_pk_fma_f32 v[34:35], v[24:25], v[12:13], v[34:35]
	v_pk_fma_f32 v[66:67], v[24:25], v[60:61], v[66:67]
	ds_read_b128 v[50:53], v38 offset:17760
	ds_read_b128 v[46:49], v38 offset:17504
	ds_read_b32 v62, v39 offset:18528
	ds_read_b128 v[54:57], v38 offset:18016
	ds_read_b128 v[58:61], v38 offset:18272
	v_add_f32_e32 v34, v34, v35
	v_add_f32_e32 v66, v66, v67
	v_pk_fma_f32 v[22:23], v[6:7], v[28:29], v[22:23] op_sel_hi:[1,0,1]
	v_add_f32_dpp v34, v34, v34 row_ror:1 row_mask:0xf bank_mask:0xf bound_ctrl:1
	v_add_f32_dpp v66, v66, v66 row_ror:1 row_mask:0xf bank_mask:0xf bound_ctrl:1
	v_pk_fma_f32 v[24:25], v[8:9], v[28:29], v[24:25] op_sel_hi:[1,0,1]
	v_add_f32_dpp v34, v34, v34 row_ror:2 row_mask:0xf bank_mask:0xf bound_ctrl:1
	v_add_f32_dpp v66, v66, v66 row_ror:2 row_mask:0xf bank_mask:0xf bound_ctrl:1
	ds_write2st64_b32 v41, v36, v66 offset0:8 offset1:9
	v_add_f32_dpp v34, v34, v34 row_ror:4 row_mask:0xf bank_mask:0xf bound_ctrl:1
	s_waitcnt lgkmcnt(7)
	s_nop 0
	s_nop 0
	v_add_f32_dpp v34, v34, v34 row_ror:8 row_mask:0xf bank_mask:0xf bound_ctrl:1
	v_pk_fma_f32 v[22:23], v[14:15], v[34:35], v[22:23] op_sel_hi:[1,0,1]
	v_pk_fma_f32 v[24:25], v[16:17], v[34:35], v[24:25] op_sel_hi:[1,0,1]
	s_waitcnt lgkmcnt(3)
	v_pk_mul_f32 v[34:35], v[22:23], v[50:51]
	v_pk_mul_f32 v[36:37], v[22:23], v[18:19]
	v_pk_fma_f32 v[34:35], v[24:25], v[52:53], v[34:35]
	v_pk_fma_f32 v[36:37], v[24:25], v[20:21], v[36:37]
	ds_read_b128 v[10:13], v38 offset:19328
	ds_read_b128 v[6:9], v38 offset:19072
	ds_read_b32 v28, v39 offset:20096
	ds_read_b128 v[14:17], v38 offset:19584
	ds_read_b128 v[18:21], v38 offset:19840
	v_add_f32_e32 v34, v34, v35
	v_add_f32_e32 v36, v36, v37
	v_pk_fma_f32 v[22:23], v[46:47], v[62:63], v[22:23] op_sel_hi:[1,0,1]
	v_add_f32_dpp v34, v34, v34 row_ror:1 row_mask:0xf bank_mask:0xf bound_ctrl:1
	v_add_f32_dpp v36, v36, v36 row_ror:1 row_mask:0xf bank_mask:0xf bound_ctrl:1
	v_pk_fma_f32 v[24:25], v[48:49], v[62:63], v[24:25] op_sel_hi:[1,0,1]
	v_add_f32_dpp v34, v34, v34 row_ror:2 row_mask:0xf bank_mask:0xf bound_ctrl:1
	v_add_f32_dpp v36, v36, v36 row_ror:2 row_mask:0xf bank_mask:0xf bound_ctrl:1
	s_nop 0
	v_add_f32_dpp v34, v34, v34 row_ror:4 row_mask:0xf bank_mask:0xf bound_ctrl:1
	s_waitcnt lgkmcnt(7)
	s_nop 0
	s_nop 0
	v_add_f32_dpp v34, v34, v34 row_ror:8 row_mask:0xf bank_mask:0xf bound_ctrl:1
	v_pk_fma_f32 v[22:23], v[54:55], v[34:35], v[22:23] op_sel_hi:[1,0,1]
	v_pk_fma_f32 v[24:25], v[56:57], v[34:35], v[24:25] op_sel_hi:[1,0,1]
	s_waitcnt lgkmcnt(2)
; #define LAS __attribute__((address_space(3)))
; template <int CTRL> __device__ __forceinline__ float dpp_f(float x) { return __int_as_float(__builtin_amdgcn_update_dpp(0, __float_as_int(x), CTRL, 0xf, 0xf, false)); }
; __device__ __forceinline__ void p8_scan(const Args& a, LAS unsigned char* lds) {
;     ...
;             for (int c = 0; c < T / TC; ++c) {
;                 const int cur = c & 1;
;                 const LAS float* bt = buf + cur * TC * SPITCH;
;                 LAS float* yd = holds_y ? (ybuf + cur * TC * 64 + 4 * (4 * w + (lane >> 4)) + ((lane & 15) >> 2)) : (dump + lane);
;                 ScanOps o; scan_ld(o, bt, jq4, myrow);
; #pragma unroll 16
;                 for (int tt = 0; tt < TC; ++tt) {
;                     ScanOps n; scan_ld(n, bt + (tt + 1 < TC ? tt + 1 : tt) * SPITCH, jq4, myrow);
;                     __builtin_amdgcn_sched_barrier(0);
;                     f32x2 ta = S01 * o.al.lo, ty = S01 * o.wr.lo; ta = S23 * o.al.hi + ta; ty = S23 * o.wr.hi + ty;
;                     float pa = ta.x + ta.y, py = ty.x + ty.y;
;                     f32x2 kv01 = o.kv.lo * o.vi, kv23 = o.kv.hi * o.vi;
;     ...
;                     asm volatile("" : "+v"(kv01), "+v"(kv23), "+v"(vc));
;                     pa += dpp_f<0x121>(pa); py += dpp_f<0x121>(py); pa += dpp_f<0x122>(pa); py += dpp_f<0x122>(py);
;                     pa += dpp_f<0x124>(pa); pa += dpp_f<0x128>(pa);
;                     S01 = S01 * o.wv.lo + (o.be.lo * pa + kv01);
;                     S23 = S23 * o.wv.hi + (o.be.hi * pa + kv23);
;     ...
;                     __builtin_amdgcn_sched_barrier(0);
;                     o = n;
;                 }
;                 __syncthreads();
	v_pk_mul_f32 v[34:35], v[22:23], v[10:11]
	v_pk_mul_f32 v[66:67], v[22:23], v[58:59]
	v_pk_fma_f32 v[34:35], v[24:25], v[12:13], v[34:35]
	v_pk_fma_f32 v[66:67], v[24:25], v[60:61], v[66:67]
	ds_read_b128 v[50:53], v38 offset:20896
	ds_read_b128 v[46:49], v38 offset:20640
	ds_read_b32 v62, v39 offset:21664
	ds_read_b128 v[54:57], v38 offset:21152
	ds_read_b128 v[58:61], v38 offset:21408
	v_add_f32_e32 v34, v34, v35
	v_add_f32_e32 v66, v66, v67
	v_pk_fma_f32 v[22:23], v[6:7], v[28:29], v[22:23] op_sel_hi:[1,0,1]
	v_add_f32_dpp v34, v34, v34 row_ror:1 row_mask:0xf bank_mask:0xf bound_ctrl:1
	v_add_f32_dpp v66, v66, v66 row_ror:1 row_mask:0xf bank_mask:0xf bound_ctrl:1
	v_pk_fma_f32 v[24:25], v[8:9], v[28:29], v[24:25] op_sel_hi:[1,0,1]
	v_add_f32_dpp v34, v34, v34 row_ror:2 row_mask:0xf bank_mask:0xf bound_ctrl:1
	v_add_f32_dpp v66, v66, v66 row_ror:2 row_mask:0xf bank_mask:0xf bound_ctrl:1
	ds_write2st64_b32 v41, v36, v66 offset0:10 offset1:11
	v_add_f32_dpp v34, v34, v34 row_ror:4 row_mask:0xf bank_mask:0xf bound_ctrl:1
	s_waitcnt lgkmcnt(7)
	s_nop 0
	s_nop 0
	v_add_f32_dpp v34, v34, v34 row_ror:8 row_mask:0xf bank_mask:0xf bound_ctrl:1
	v_pk_fma_f32 v[22:23], v[14:15], v[34:35], v[22:23] op_sel_hi:[1,0,1]
	v_pk_fma_f32 v[24:25], v[16:17], v[34:35], v[24:25] op_sel_hi:[1,0,1]
	s_waitcnt lgkmcnt(3)
	v_pk_mul_f32 v[34:35], v[22:23], v[50:51]
	v_pk_mul_f32 v[36:37], v[22:23], v[18:19]
	v_pk_fma_f32 v[34:35], v[24:25], v[52:53], v[34:35]
	v_pk_fma_f32 v[36:37], v[24:25], v[20:21], v[36:37]
	ds_read_b128 v[10:13], v38 offset:22464
	ds_read_b128 v[6:9], v38 offset:22208
	ds_read_b32 v28, v39 offset:23232
	ds_read_b128 v[14:17], v38 offset:22720
	ds_read_b128 v[18:21], v38 offset:22976
	v_add_f32_e32 v34, v34, v35
	v_add_f32_e32 v36, v36, v37
	v_pk_fma_f32 v[22:23], v[46:47], v[62:63], v[22:23] op_sel_hi:[1,0,1]
	v_add_f32_dpp v34, v34, v34 row_ror:1 row_mask:0xf bank_mask:0xf bound_ctrl:1
	v_add_f32_dpp v36, v36, v36 row_ror:1 row_mask:0xf bank_mask:0xf bound_ctrl:1
	v_pk_fma_f32 v[24:25], v[48:49], v[62:63], v[24:25] op_sel_hi:[1,0,1]
	v_add_f32_dpp v34, v34, v34 row_ror:2 row_mask:0xf bank_mask:0xf bound_ctrl:1
	v_add_f32_dpp v36, v36, v36 row_ror:2 row_mask:0xf bank_mask:0xf bound_ctrl:1
	s_nop 0
	v_add_f32_dpp v34, v34, v34 row_ror:4 row_mask:0xf bank_mask:0xf bound_ctrl:1
	s_waitcnt lgkmcnt(7)
	s_nop 0
	s_nop 0
	v_add_f32_dpp v34, v34, v34 row_ror:8 row_mask:0xf bank_mask:0xf bound_ctrl:1
	v_pk_fma_f32 v[22:23], v[54:55], v[34:35], v[22:23] op_sel_hi:[1,0,1]
	v_pk_fma_f32 v[24:25], v[56:57], v[34:35], v[24:25] op_sel_hi:[1,0,1]
	s_waitcnt lgkmcnt(2)
	v_pk_mul_f32 v[34:35], v[22:23], v[10:11]
	v_pk_mul_f32 v[66:67], v[22:23], v[58:59]
	v_pk_fma_f32 v[34:35], v[24:25], v[12:13], v[34:35]
	v_pk_fma_f32 v[66:67], v[24:25], v[60:61], v[66:67]
	ds_read_b128 v[50:53], v38 offset:24032
	ds_read_b128 v[46:49], v38 offset:23776
	ds_read_b32 v62, v39 offset:24800
	ds_read_b128 v[42:45], v38 offset:23520
	ds_read_b128 v[54:57], v38 offset:24288
	ds_read_b128 v[58:61], v38 offset:24544
	v_add_f32_e32 v34, v34, v35
	v_add_f32_e32 v66, v66, v67
	v_pk_fma_f32 v[22:23], v[6:7], v[28:29], v[22:23] op_sel_hi:[1,0,1]
	v_add_f32_dpp v34, v34, v34 row_ror:1 row_mask:0xf bank_mask:0xf bound_ctrl:1
	v_add_f32_dpp v66, v66, v66 row_ror:1 row_mask:0xf bank_mask:0xf bound_ctrl:1
	v_pk_fma_f32 v[24:25], v[8:9], v[28:29], v[24:25] op_sel_hi:[1,0,1]
	v_add_f32_dpp v34, v34, v34 row_ror:2 row_mask:0xf bank_mask:0xf bound_ctrl:1
	v_add_f32_dpp v66, v66, v66 row_ror:2 row_mask:0xf bank_mask:0xf bound_ctrl:1
	ds_write2st64_b32 v41, v36, v66 offset0:12 offset1:13
	v_add_f32_dpp v34, v34, v34 row_ror:4 row_mask:0xf bank_mask:0xf bound_ctrl:1
	s_waitcnt lgkmcnt(8)
	s_nop 0
	s_nop 0
	v_add_f32_dpp v34, v34, v34 row_ror:8 row_mask:0xf bank_mask:0xf bound_ctrl:1
	v_pk_fma_f32 v[22:23], v[14:15], v[34:35], v[22:23] op_sel_hi:[1,0,1]
	v_pk_fma_f32 v[24:25], v[16:17], v[34:35], v[24:25] op_sel_hi:[1,0,1]
	s_waitcnt lgkmcnt(4)
	v_pk_mul_f32 v[34:35], v[22:23], v[50:51]
	v_pk_mul_f32 v[36:37], v[22:23], v[18:19]
	v_pk_fma_f32 v[34:35], v[24:25], v[52:53], v[34:35]
	v_pk_fma_f32 v[36:37], v[24:25], v[20:21], v[36:37]
	ds_read_b128 v[10:13], v38 offset:25600
	ds_read_b128 v[6:9], v38 offset:25344
	ds_read_b32 v28, v39 offset:26368
	ds_read_b128 v[14:17], v38 offset:25856
	ds_read_b128 v[18:21], v38 offset:26112
	v_add_f32_e32 v34, v34, v35
	v_add_f32_e32 v36, v36, v37
	v_pk_fma_f32 v[22:23], v[46:47], v[62:63], v[22:23] op_sel_hi:[1,0,1]
	v_add_f32_dpp v34, v34, v34 row_ror:1 row_mask:0xf bank_mask:0xf bound_ctrl:1
	v_add_f32_dpp v36, v36, v36 row_ror:1 row_mask:0xf bank_mask:0xf bound_ctrl:1
	v_pk_fma_f32 v[24:25], v[48:49], v[62:63], v[24:25] op_sel_hi:[1,0,1]
	v_add_f32_dpp v34, v34, v34 row_ror:2 row_mask:0xf bank_mask:0xf bound_ctrl:1
	v_add_f32_dpp v36, v36, v36 row_ror:2 row_mask:0xf bank_mask:0xf bound_ctrl:1
	s_nop 0
	v_add_f32_dpp v34, v34, v34 row_ror:4 row_mask:0xf bank_mask:0xf bound_ctrl:1
	s_waitcnt lgkmcnt(7)
	s_nop 0
	s_nop 0
	v_add_f32_dpp v34, v34, v34 row_ror:8 row_mask:0xf bank_mask:0xf bound_ctrl:1
	v_pk_fma_f32 v[22:23], v[54:55], v[34:35], v[22:23] op_sel_hi:[1,0,1]
	v_pk_fma_f32 v[24:25], v[56:57], v[34:35], v[24:25] op_sel_hi:[1,0,1]
	s_waitcnt lgkmcnt(2)
; #define LAS __attribute__((address_space(3)))
; template <int CTRL> __device__ __forceinline__ float dpp_f(float x) { return __int_as_float(__builtin_amdgcn_update_dpp(0, __float_as_int(x), CTRL, 0xf, 0xf, false)); }
; __device__ __forceinline__ void p8_scan(const Args& a, LAS unsigned char* lds) {
;     ...
;             for (int c = 0; c < T / TC; ++c) {
;                 const int cur = c & 1;
;                 const LAS float* bt = buf + cur * TC * SPITCH;
;                 LAS float* yd = holds_y ? (ybuf + cur * TC * 64 + 4 * (4 * w + (lane >> 4)) + ((lane & 15) >> 2)) : (dump + lane);
;                 ScanOps o; scan_ld(o, bt, jq4, myrow);
; #pragma unroll 16
;                 for (int tt = 0; tt < TC; ++tt) {
;                     ScanOps n; scan_ld(n, bt + (tt + 1 < TC ? tt + 1 : tt) * SPITCH, jq4, myrow);
;                     __builtin_amdgcn_sched_barrier(0);
;                     f32x2 ta = S01 * o.al.lo, ty = S01 * o.wr.lo; ta = S23 * o.al.hi + ta; ty = S23 * o.wr.hi + ty;
;                     float pa = ta.x + ta.y, py = ty.x + ty.y;
;                     f32x2 kv01 = o.kv.lo * o.vi, kv23 = o.kv.hi * o.vi;
;     ...
;                     asm volatile("" : "+v"(kv01), "+v"(kv23), "+v"(vc));
;                     pa += dpp_f<0x121>(pa); py += dpp_f<0x121>(py); pa += dpp_f<0x122>(pa); py += dpp_f<0x122>(py);
;                     pa += dpp_f<0x124>(pa); pa += dpp_f<0x128>(pa);
;                     S01 = S01 * o.wv.lo + (o.be.lo * pa + kv01);
;                     S23 = S23 * o.wv.hi + (o.be.hi * pa + kv23);
;     ...
;                     __builtin_amdgcn_sched_barrier(0);
;                     o = n;
;                 }
;                 __syncthreads();
	v_pk_mul_f32 v[66:67], v[22:23], v[58:59]
	v_pk_fma_f32 v[66:67], v[24:25], v[60:61], v[66:67]
	v_pk_mul_f32 v[22:23], v[22:23], v[42:43]
	v_pk_mul_f32 v[24:25], v[24:25], v[44:45]
	v_pk_mul_f32 v[34:35], v[22:23], v[10:11]
	v_pk_fma_f32 v[34:35], v[24:25], v[12:13], v[34:35]
	ds_read_b128 v[50:53], v38 offset:27168
	ds_read_b128 v[46:49], v38 offset:26912
	ds_read_b32 v62, v39 offset:27936
	ds_read_b128 v[54:57], v38 offset:27424
	ds_read_b128 v[58:61], v38 offset:27680
	v_add_f32_e32 v34, v34, v35
	v_add_f32_e32 v66, v66, v67
	v_pk_fma_f32 v[22:23], v[6:7], v[28:29], v[22:23] op_sel_hi:[1,0,1]
	v_add_f32_dpp v34, v34, v34 row_ror:1 row_mask:0xf bank_mask:0xf bound_ctrl:1
	v_add_f32_dpp v66, v66, v66 row_ror:1 row_mask:0xf bank_mask:0xf bound_ctrl:1
	v_pk_fma_f32 v[24:25], v[8:9], v[28:29], v[24:25] op_sel_hi:[1,0,1]
	v_add_f32_dpp v34, v34, v34 row_ror:2 row_mask:0xf bank_mask:0xf bound_ctrl:1
	v_add_f32_dpp v66, v66, v66 row_ror:2 row_mask:0xf bank_mask:0xf bound_ctrl:1
	ds_write2st64_b32 v41, v36, v66 offset0:14 offset1:15
	v_add_f32_dpp v34, v34, v34 row_ror:4 row_mask:0xf bank_mask:0xf bound_ctrl:1
	s_waitcnt lgkmcnt(7)
	s_nop 0
	s_nop 0
	v_add_f32_dpp v34, v34, v34 row_ror:8 row_mask:0xf bank_mask:0xf bound_ctrl:1
	v_pk_fma_f32 v[22:23], v[14:15], v[34:35], v[22:23] op_sel_hi:[1,0,1]
	v_pk_fma_f32 v[24:25], v[16:17], v[34:35], v[24:25] op_sel_hi:[1,0,1]
	s_waitcnt lgkmcnt(3)
	v_pk_mul_f32 v[34:35], v[22:23], v[50:51]
	v_pk_mul_f32 v[36:37], v[22:23], v[18:19]
	v_pk_fma_f32 v[34:35], v[24:25], v[52:53], v[34:35]
	v_pk_fma_f32 v[36:37], v[24:25], v[20:21], v[36:37]
	ds_read_b128 v[10:13], v38 offset:28736
	ds_read_b128 v[6:9], v38 offset:28480
	ds_read_b32 v28, v39 offset:29504
	ds_read_b128 v[14:17], v38 offset:28992
	ds_read_b128 v[18:21], v38 offset:29248
	v_add_f32_e32 v34, v34, v35
	v_add_f32_e32 v36, v36, v37
	v_pk_fma_f32 v[22:23], v[46:47], v[62:63], v[22:23] op_sel_hi:[1,0,1]
	v_add_f32_dpp v34, v34, v34 row_ror:1 row_mask:0xf bank_mask:0xf bound_ctrl:1
	v_add_f32_dpp v36, v36, v36 row_ror:1 row_mask:0xf bank_mask:0xf bound_ctrl:1
	v_pk_fma_f32 v[24:25], v[48:49], v[62:63], v[24:25] op_sel_hi:[1,0,1]
	v_add_f32_dpp v34, v34, v34 row_ror:2 row_mask:0xf bank_mask:0xf bound_ctrl:1
	v_add_f32_dpp v36, v36, v36 row_ror:2 row_mask:0xf bank_mask:0xf bound_ctrl:1
	s_nop 0
	v_add_f32_dpp v34, v34, v34 row_ror:4 row_mask:0xf bank_mask:0xf bound_ctrl:1
	s_waitcnt lgkmcnt(7)
	s_nop 0
	s_nop 0
	v_add_f32_dpp v34, v34, v34 row_ror:8 row_mask:0xf bank_mask:0xf bound_ctrl:1
	v_pk_fma_f32 v[22:23], v[54:55], v[34:35], v[22:23] op_sel_hi:[1,0,1]
	v_pk_fma_f32 v[24:25], v[56:57], v[34:35], v[24:25] op_sel_hi:[1,0,1]
	s_waitcnt lgkmcnt(2)
	v_pk_mul_f32 v[34:35], v[22:23], v[10:11]
	v_pk_mul_f32 v[66:67], v[22:23], v[58:59]
	v_pk_fma_f32 v[34:35], v[24:25], v[12:13], v[34:35]
	v_pk_fma_f32 v[66:67], v[24:25], v[60:61], v[66:67]
	ds_read_b128 v[50:53], v38 offset:30304
	ds_read_b128 v[46:49], v38 offset:30048
	ds_read_b32 v62, v39 offset:31072
	ds_read_b128 v[54:57], v38 offset:30560
	ds_read_b128 v[58:61], v38 offset:30816
	v_add_f32_e32 v34, v34, v35
	v_add_f32_e32 v66, v66, v67
	v_pk_fma_f32 v[22:23], v[6:7], v[28:29], v[22:23] op_sel_hi:[1,0,1]
	v_add_f32_dpp v34, v34, v34 row_ror:1 row_mask:0xf bank_mask:0xf bound_ctrl:1
	v_add_f32_dpp v66, v66, v66 row_ror:1 row_mask:0xf bank_mask:0xf bound_ctrl:1
	v_pk_fma_f32 v[24:25], v[8:9], v[28:29], v[24:25] op_sel_hi:[1,0,1]
	v_add_f32_dpp v34, v34, v34 row_ror:2 row_mask:0xf bank_mask:0xf bound_ctrl:1
	v_add_f32_dpp v66, v66, v66 row_ror:2 row_mask:0xf bank_mask:0xf bound_ctrl:1
	ds_write2st64_b32 v41, v36, v66 offset0:16 offset1:17
	v_add_f32_dpp v34, v34, v34 row_ror:4 row_mask:0xf bank_mask:0xf bound_ctrl:1
	s_waitcnt lgkmcnt(7)
	s_nop 0
	s_nop 0
	v_add_f32_dpp v34, v34, v34 row_ror:8 row_mask:0xf bank_mask:0xf bound_ctrl:1
	v_pk_fma_f32 v[22:23], v[14:15], v[34:35], v[22:23] op_sel_hi:[1,0,1]
	v_pk_fma_f32 v[24:25], v[16:17], v[34:35], v[24:25] op_sel_hi:[1,0,1]
	s_waitcnt lgkmcnt(3)
	v_pk_mul_f32 v[34:35], v[22:23], v[50:51]
	v_pk_mul_f32 v[36:37], v[22:23], v[18:19]
	v_pk_fma_f32 v[34:35], v[24:25], v[52:53], v[34:35]
	v_pk_fma_f32 v[36:37], v[24:25], v[20:21], v[36:37]
	ds_read_b128 v[10:13], v38 offset:31872
	ds_read_b128 v[6:9], v38 offset:31616
	ds_read_b32 v28, v39 offset:32640
	ds_read_b128 v[14:17], v38 offset:32128
	ds_read_b128 v[18:21], v38 offset:32384
	v_add_f32_e32 v34, v34, v35
	v_add_f32_e32 v36, v36, v37
	v_pk_fma_f32 v[22:23], v[46:47], v[62:63], v[22:23] op_sel_hi:[1,0,1]
	v_add_f32_dpp v34, v34, v34 row_ror:1 row_mask:0xf bank_mask:0xf bound_ctrl:1
	v_add_f32_dpp v36, v36, v36 row_ror:1 row_mask:0xf bank_mask:0xf bound_ctrl:1
	v_pk_fma_f32 v[24:25], v[48:49], v[62:63], v[24:25] op_sel_hi:[1,0,1]
	v_add_f32_dpp v34, v34, v34 row_ror:2 row_mask:0xf bank_mask:0xf bound_ctrl:1
	v_add_f32_dpp v36, v36, v36 row_ror:2 row_mask:0xf bank_mask:0xf bound_ctrl:1
	s_nop 0
	v_add_f32_dpp v34, v34, v34 row_ror:4 row_mask:0xf bank_mask:0xf bound_ctrl:1
	s_waitcnt lgkmcnt(7)
	s_nop 0
	s_nop 0
	v_add_f32_dpp v34, v34, v34 row_ror:8 row_mask:0xf bank_mask:0xf bound_ctrl:1
	v_pk_fma_f32 v[22:23], v[54:55], v[34:35], v[22:23] op_sel_hi:[1,0,1]
	v_pk_fma_f32 v[24:25], v[56:57], v[34:35], v[24:25] op_sel_hi:[1,0,1]
	s_waitcnt lgkmcnt(2)
; #define LAS __attribute__((address_space(3)))
; template <int CTRL> __device__ __forceinline__ float dpp_f(float x) { return __int_as_float(__builtin_amdgcn_update_dpp(0, __float_as_int(x), CTRL, 0xf, 0xf, false)); }
; __device__ __forceinline__ void p8_scan(const Args& a, LAS unsigned char* lds) {
;     ...
;             for (int c = 0; c < T / TC; ++c) {
;                 const int cur = c & 1;
;                 const LAS float* bt = buf + cur * TC * SPITCH;
;                 LAS float* yd = holds_y ? (ybuf + cur * TC * 64 + 4 * (4 * w + (lane >> 4)) + ((lane & 15) >> 2)) : (dump + lane);
;                 ScanOps o; scan_ld(o, bt, jq4, myrow);
; #pragma unroll 16
;                 for (int tt = 0; tt < TC; ++tt) {
;                     ScanOps n; scan_ld(n, bt + (tt + 1 < TC ? tt + 1 : tt) * SPITCH, jq4, myrow);
;                     __builtin_amdgcn_sched_barrier(0);
;                     f32x2 ta = S01 * o.al.lo, ty = S01 * o.wr.lo; ta = S23 * o.al.hi + ta; ty = S23 * o.wr.hi + ty;
;                     float pa = ta.x + ta.y, py = ty.x + ty.y;
;                     f32x2 kv01 = o.kv.lo * o.vi, kv23 = o.kv.hi * o.vi;
;     ...
;                     asm volatile("" : "+v"(kv01), "+v"(kv23), "+v"(vc));
;                     pa += dpp_f<0x121>(pa); py += dpp_f<0x121>(py); pa += dpp_f<0x122>(pa); py += dpp_f<0x122>(py);
;                     pa += dpp_f<0x124>(pa); pa += dpp_f<0x128>(pa);
;                     S01 = S01 * o.wv.lo + (o.be.lo * pa + kv01);
;                     S23 = S23 * o.wv.hi + (o.be.hi * pa + kv23);
;     ...
;                     __builtin_amdgcn_sched_barrier(0);
;                     o = n;
;                 }
;                 __syncthreads();
	v_pk_mul_f32 v[34:35], v[22:23], v[10:11]
	v_pk_mul_f32 v[66:67], v[22:23], v[58:59]
	v_pk_fma_f32 v[34:35], v[24:25], v[12:13], v[34:35]
	v_pk_fma_f32 v[66:67], v[24:25], v[60:61], v[66:67]
	ds_read_b128 v[50:53], v38 offset:33440
	ds_read_b128 v[46:49], v38 offset:33184
	ds_read_b32 v62, v39 offset:34208
	ds_read_b128 v[54:57], v38 offset:33696
	ds_read_b128 v[58:61], v38 offset:33952
	v_add_f32_e32 v34, v34, v35
	v_add_f32_e32 v66, v66, v67
	v_pk_fma_f32 v[22:23], v[6:7], v[28:29], v[22:23] op_sel_hi:[1,0,1]
	v_add_f32_dpp v34, v34, v34 row_ror:1 row_mask:0xf bank_mask:0xf bound_ctrl:1
	v_add_f32_dpp v66, v66, v66 row_ror:1 row_mask:0xf bank_mask:0xf bound_ctrl:1
	v_pk_fma_f32 v[24:25], v[8:9], v[28:29], v[24:25] op_sel_hi:[1,0,1]
	v_add_f32_dpp v34, v34, v34 row_ror:2 row_mask:0xf bank_mask:0xf bound_ctrl:1
	v_add_f32_dpp v66, v66, v66 row_ror:2 row_mask:0xf bank_mask:0xf bound_ctrl:1
	ds_write2st64_b32 v41, v36, v66 offset0:18 offset1:19
	v_add_f32_dpp v34, v34, v34 row_ror:4 row_mask:0xf bank_mask:0xf bound_ctrl:1
	s_waitcnt lgkmcnt(7)
	s_nop 0
	s_nop 0
	v_add_f32_dpp v34, v34, v34 row_ror:8 row_mask:0xf bank_mask:0xf bound_ctrl:1
	v_pk_fma_f32 v[22:23], v[14:15], v[34:35], v[22:23] op_sel_hi:[1,0,1]
	v_pk_fma_f32 v[24:25], v[16:17], v[34:35], v[24:25] op_sel_hi:[1,0,1]
	s_waitcnt lgkmcnt(3)
	v_pk_mul_f32 v[34:35], v[22:23], v[50:51]
	v_pk_mul_f32 v[36:37], v[22:23], v[18:19]
	v_pk_fma_f32 v[34:35], v[24:25], v[52:53], v[34:35]
	v_pk_fma_f32 v[36:37], v[24:25], v[20:21], v[36:37]
	ds_read_b128 v[10:13], v38 offset:35008
	ds_read_b128 v[6:9], v38 offset:34752
	ds_read_b32 v28, v39 offset:35776
	ds_read_b128 v[14:17], v38 offset:35264
	ds_read_b128 v[18:21], v38 offset:35520
	v_add_f32_e32 v34, v34, v35
	v_add_f32_e32 v36, v36, v37
	v_pk_fma_f32 v[22:23], v[46:47], v[62:63], v[22:23] op_sel_hi:[1,0,1]
	v_add_f32_dpp v34, v34, v34 row_ror:1 row_mask:0xf bank_mask:0xf bound_ctrl:1
	v_add_f32_dpp v36, v36, v36 row_ror:1 row_mask:0xf bank_mask:0xf bound_ctrl:1
	v_pk_fma_f32 v[24:25], v[48:49], v[62:63], v[24:25] op_sel_hi:[1,0,1]
	v_add_f32_dpp v34, v34, v34 row_ror:2 row_mask:0xf bank_mask:0xf bound_ctrl:1
	v_add_f32_dpp v36, v36, v36 row_ror:2 row_mask:0xf bank_mask:0xf bound_ctrl:1
	s_nop 0
	v_add_f32_dpp v34, v34, v34 row_ror:4 row_mask:0xf bank_mask:0xf bound_ctrl:1
	s_waitcnt lgkmcnt(7)
	s_nop 0
	s_nop 0
	v_add_f32_dpp v34, v34, v34 row_ror:8 row_mask:0xf bank_mask:0xf bound_ctrl:1
	v_pk_fma_f32 v[22:23], v[54:55], v[34:35], v[22:23] op_sel_hi:[1,0,1]
	v_pk_fma_f32 v[24:25], v[56:57], v[34:35], v[24:25] op_sel_hi:[1,0,1]
	s_waitcnt lgkmcnt(2)
	v_pk_mul_f32 v[34:35], v[22:23], v[10:11]
	v_pk_mul_f32 v[66:67], v[22:23], v[58:59]
	v_pk_fma_f32 v[34:35], v[24:25], v[12:13], v[34:35]
	v_pk_fma_f32 v[66:67], v[24:25], v[60:61], v[66:67]
	ds_read_b128 v[50:53], v38 offset:36576
	ds_read_b128 v[46:49], v38 offset:36320
	ds_read_b32 v62, v39 offset:37344
	ds_read_b128 v[42:45], v38 offset:36064
	ds_read_b128 v[54:57], v38 offset:36832
	ds_read_b128 v[58:61], v38 offset:37088
	v_add_f32_e32 v34, v34, v35
	v_add_f32_e32 v66, v66, v67
	v_pk_fma_f32 v[22:23], v[6:7], v[28:29], v[22:23] op_sel_hi:[1,0,1]
	v_add_f32_dpp v34, v34, v34 row_ror:1 row_mask:0xf bank_mask:0xf bound_ctrl:1
	v_add_f32_dpp v66, v66, v66 row_ror:1 row_mask:0xf bank_mask:0xf bound_ctrl:1
	v_pk_fma_f32 v[24:25], v[8:9], v[28:29], v[24:25] op_sel_hi:[1,0,1]
	v_add_f32_dpp v34, v34, v34 row_ror:2 row_mask:0xf bank_mask:0xf bound_ctrl:1
	v_add_f32_dpp v66, v66, v66 row_ror:2 row_mask:0xf bank_mask:0xf bound_ctrl:1
	ds_write2st64_b32 v41, v36, v66 offset0:20 offset1:21
	v_add_f32_dpp v34, v34, v34 row_ror:4 row_mask:0xf bank_mask:0xf bound_ctrl:1
	s_waitcnt lgkmcnt(8)
	s_nop 0
	s_nop 0
	v_add_f32_dpp v34, v34, v34 row_ror:8 row_mask:0xf bank_mask:0xf bound_ctrl:1
	v_pk_fma_f32 v[22:23], v[14:15], v[34:35], v[22:23] op_sel_hi:[1,0,1]
	v_pk_fma_f32 v[24:25], v[16:17], v[34:35], v[24:25] op_sel_hi:[1,0,1]
	s_waitcnt lgkmcnt(4)
	v_pk_mul_f32 v[34:35], v[22:23], v[50:51]
	v_pk_mul_f32 v[36:37], v[22:23], v[18:19]
	v_pk_fma_f32 v[34:35], v[24:25], v[52:53], v[34:35]
	v_pk_fma_f32 v[36:37], v[24:25], v[20:21], v[36:37]
	ds_read_b128 v[10:13], v38 offset:38144
	ds_read_b128 v[6:9], v38 offset:37888
	ds_read_b32 v28, v39 offset:38912
	ds_read_b128 v[14:17], v38 offset:38400
	ds_read_b128 v[18:21], v38 offset:38656
	v_add_f32_e32 v34, v34, v35
	v_add_f32_e32 v36, v36, v37
	v_pk_fma_f32 v[22:23], v[46:47], v[62:63], v[22:23] op_sel_hi:[1,0,1]
	v_add_f32_dpp v34, v34, v34 row_ror:1 row_mask:0xf bank_mask:0xf bound_ctrl:1
	v_add_f32_dpp v36, v36, v36 row_ror:1 row_mask:0xf bank_mask:0xf bound_ctrl:1
	v_pk_fma_f32 v[24:25], v[48:49], v[62:63], v[24:25] op_sel_hi:[1,0,1]
	v_add_f32_dpp v34, v34, v34 row_ror:2 row_mask:0xf bank_mask:0xf bound_ctrl:1
	v_add_f32_dpp v36, v36, v36 row_ror:2 row_mask:0xf bank_mask:0xf bound_ctrl:1
	s_nop 0
	v_add_f32_dpp v34, v34, v34 row_ror:4 row_mask:0xf bank_mask:0xf bound_ctrl:1
	s_waitcnt lgkmcnt(7)
	s_nop 0
	s_nop 0
	v_add_f32_dpp v34, v34, v34 row_ror:8 row_mask:0xf bank_mask:0xf bound_ctrl:1
	v_pk_fma_f32 v[22:23], v[54:55], v[34:35], v[22:23] op_sel_hi:[1,0,1]
	v_pk_fma_f32 v[24:25], v[56:57], v[34:35], v[24:25] op_sel_hi:[1,0,1]
	s_waitcnt lgkmcnt(2)
; #define LAS __attribute__((address_space(3)))
; template <int CTRL> __device__ __forceinline__ float dpp_f(float x) { return __int_as_float(__builtin_amdgcn_update_dpp(0, __float_as_int(x), CTRL, 0xf, 0xf, false)); }
; __device__ __forceinline__ void p8_scan(const Args& a, LAS unsigned char* lds) {
;     ...
;             for (int c = 0; c < T / TC; ++c) {
;                 const int cur = c & 1;
;                 const LAS float* bt = buf + cur * TC * SPITCH;
;                 LAS float* yd = holds_y ? (ybuf + cur * TC * 64 + 4 * (4 * w + (lane >> 4)) + ((lane & 15) >> 2)) : (dump + lane);
;                 ScanOps o; scan_ld(o, bt, jq4, myrow);
; #pragma unroll 16
;                 for (int tt = 0; tt < TC; ++tt) {
;                     ScanOps n; scan_ld(n, bt + (tt + 1 < TC ? tt + 1 : tt) * SPITCH, jq4, myrow);
;                     __builtin_amdgcn_sched_barrier(0);
;                     f32x2 ta = S01 * o.al.lo, ty = S01 * o.wr.lo; ta = S23 * o.al.hi + ta; ty = S23 * o.wr.hi + ty;
;                     float pa = ta.x + ta.y, py = ty.x + ty.y;
;                     f32x2 kv01 = o.kv.lo * o.vi, kv23 = o.kv.hi * o.vi;
;     ...
;                     asm volatile("" : "+v"(kv01), "+v"(kv23), "+v"(vc));
;                     pa += dpp_f<0x121>(pa); py += dpp_f<0x121>(py); pa += dpp_f<0x122>(pa); py += dpp_f<0x122>(py);
;                     pa += dpp_f<0x124>(pa); pa += dpp_f<0x128>(pa);
;                     S01 = S01 * o.wv.lo + (o.be.lo * pa + kv01);
;                     S23 = S23 * o.wv.hi + (o.be.hi * pa + kv23);
;     ...
;                     __builtin_amdgcn_sched_barrier(0);
;                     o = n;
;                 }
;                 __syncthreads();
	v_pk_mul_f32 v[66:67], v[22:23], v[58:59]
	v_pk_fma_f32 v[66:67], v[24:25], v[60:61], v[66:67]
	v_pk_mul_f32 v[22:23], v[22:23], v[42:43]
	v_pk_mul_f32 v[24:25], v[24:25], v[44:45]
	v_pk_mul_f32 v[34:35], v[22:23], v[10:11]
	v_pk_fma_f32 v[34:35], v[24:25], v[12:13], v[34:35]
	ds_read_b128 v[50:53], v38 offset:39712
	ds_read_b128 v[46:49], v38 offset:39456
	ds_read_b32 v62, v39 offset:40480
	ds_read_b128 v[54:57], v38 offset:39968
	ds_read_b128 v[58:61], v38 offset:40224
	v_add_f32_e32 v34, v34, v35
	v_add_f32_e32 v66, v66, v67
	v_pk_fma_f32 v[22:23], v[6:7], v[28:29], v[22:23] op_sel_hi:[1,0,1]
	v_add_f32_dpp v34, v34, v34 row_ror:1 row_mask:0xf bank_mask:0xf bound_ctrl:1
	v_add_f32_dpp v66, v66, v66 row_ror:1 row_mask:0xf bank_mask:0xf bound_ctrl:1
	v_pk_fma_f32 v[24:25], v[8:9], v[28:29], v[24:25] op_sel_hi:[1,0,1]
	v_add_f32_dpp v34, v34, v34 row_ror:2 row_mask:0xf bank_mask:0xf bound_ctrl:1
	v_add_f32_dpp v66, v66, v66 row_ror:2 row_mask:0xf bank_mask:0xf bound_ctrl:1
	ds_write2st64_b32 v41, v36, v66 offset0:22 offset1:23
	v_add_f32_dpp v34, v34, v34 row_ror:4 row_mask:0xf bank_mask:0xf bound_ctrl:1
	s_waitcnt lgkmcnt(7)
	s_nop 0
	s_nop 0
	v_add_f32_dpp v34, v34, v34 row_ror:8 row_mask:0xf bank_mask:0xf bound_ctrl:1
	v_pk_fma_f32 v[22:23], v[14:15], v[34:35], v[22:23] op_sel_hi:[1,0,1]
	v_pk_fma_f32 v[24:25], v[16:17], v[34:35], v[24:25] op_sel_hi:[1,0,1]
	s_waitcnt lgkmcnt(3)
	v_pk_mul_f32 v[34:35], v[22:23], v[50:51]
	v_pk_mul_f32 v[36:37], v[22:23], v[18:19]
	v_pk_fma_f32 v[34:35], v[24:25], v[52:53], v[34:35]
	v_pk_fma_f32 v[36:37], v[24:25], v[20:21], v[36:37]
	ds_read_b128 v[10:13], v38 offset:41280
	ds_read_b128 v[6:9], v38 offset:41024
	ds_read_b32 v28, v39 offset:42048
	ds_read_b128 v[14:17], v38 offset:41536
	ds_read_b128 v[18:21], v38 offset:41792
	v_add_f32_e32 v34, v34, v35
	v_add_f32_e32 v36, v36, v37
	v_pk_fma_f32 v[22:23], v[46:47], v[62:63], v[22:23] op_sel_hi:[1,0,1]
	v_add_f32_dpp v34, v34, v34 row_ror:1 row_mask:0xf bank_mask:0xf bound_ctrl:1
	v_add_f32_dpp v36, v36, v36 row_ror:1 row_mask:0xf bank_mask:0xf bound_ctrl:1
	v_pk_fma_f32 v[24:25], v[48:49], v[62:63], v[24:25] op_sel_hi:[1,0,1]
	v_add_f32_dpp v34, v34, v34 row_ror:2 row_mask:0xf bank_mask:0xf bound_ctrl:1
	v_add_f32_dpp v36, v36, v36 row_ror:2 row_mask:0xf bank_mask:0xf bound_ctrl:1
	s_nop 0
	v_add_f32_dpp v34, v34, v34 row_ror:4 row_mask:0xf bank_mask:0xf bound_ctrl:1
	s_waitcnt lgkmcnt(7)
	s_nop 0
	s_nop 0
	v_add_f32_dpp v34, v34, v34 row_ror:8 row_mask:0xf bank_mask:0xf bound_ctrl:1
	v_pk_fma_f32 v[22:23], v[54:55], v[34:35], v[22:23] op_sel_hi:[1,0,1]
	v_pk_fma_f32 v[24:25], v[56:57], v[34:35], v[24:25] op_sel_hi:[1,0,1]
	s_waitcnt lgkmcnt(2)
	v_pk_mul_f32 v[34:35], v[22:23], v[10:11]
	v_pk_mul_f32 v[66:67], v[22:23], v[58:59]
	v_pk_fma_f32 v[34:35], v[24:25], v[12:13], v[34:35]
	v_pk_fma_f32 v[66:67], v[24:25], v[60:61], v[66:67]
	ds_read_b128 v[50:53], v38 offset:42848
	ds_read_b128 v[46:49], v38 offset:42592
	ds_read_b32 v62, v39 offset:43616
	ds_read_b128 v[54:57], v38 offset:43104
	ds_read_b128 v[58:61], v38 offset:43360
	v_add_f32_e32 v34, v34, v35
	v_add_f32_e32 v66, v66, v67
	v_pk_fma_f32 v[22:23], v[6:7], v[28:29], v[22:23] op_sel_hi:[1,0,1]
	v_add_f32_dpp v34, v34, v34 row_ror:1 row_mask:0xf bank_mask:0xf bound_ctrl:1
	v_add_f32_dpp v66, v66, v66 row_ror:1 row_mask:0xf bank_mask:0xf bound_ctrl:1
	v_pk_fma_f32 v[24:25], v[8:9], v[28:29], v[24:25] op_sel_hi:[1,0,1]
	v_add_f32_dpp v34, v34, v34 row_ror:2 row_mask:0xf bank_mask:0xf bound_ctrl:1
	v_add_f32_dpp v66, v66, v66 row_ror:2 row_mask:0xf bank_mask:0xf bound_ctrl:1
	ds_write2st64_b32 v41, v36, v66 offset0:24 offset1:25
	v_add_f32_dpp v34, v34, v34 row_ror:4 row_mask:0xf bank_mask:0xf bound_ctrl:1
	s_waitcnt lgkmcnt(7)
	s_nop 0
	s_nop 0
	v_add_f32_dpp v34, v34, v34 row_ror:8 row_mask:0xf bank_mask:0xf bound_ctrl:1
	v_pk_fma_f32 v[22:23], v[14:15], v[34:35], v[22:23] op_sel_hi:[1,0,1]
	v_pk_fma_f32 v[24:25], v[16:17], v[34:35], v[24:25] op_sel_hi:[1,0,1]
	s_waitcnt lgkmcnt(3)
	v_pk_mul_f32 v[34:35], v[22:23], v[50:51]
	v_pk_mul_f32 v[36:37], v[22:23], v[18:19]
	v_pk_fma_f32 v[34:35], v[24:25], v[52:53], v[34:35]
	v_pk_fma_f32 v[36:37], v[24:25], v[20:21], v[36:37]
	ds_read_b128 v[10:13], v38 offset:44416
	ds_read_b128 v[6:9], v38 offset:44160
	ds_read_b32 v28, v39 offset:45184
	ds_read_b128 v[14:17], v38 offset:44672
	ds_read_b128 v[18:21], v38 offset:44928
	v_add_f32_e32 v34, v34, v35
	v_add_f32_e32 v36, v36, v37
	v_pk_fma_f32 v[22:23], v[46:47], v[62:63], v[22:23] op_sel_hi:[1,0,1]
	v_add_f32_dpp v34, v34, v34 row_ror:1 row_mask:0xf bank_mask:0xf bound_ctrl:1
	v_add_f32_dpp v36, v36, v36 row_ror:1 row_mask:0xf bank_mask:0xf bound_ctrl:1
	v_pk_fma_f32 v[24:25], v[48:49], v[62:63], v[24:25] op_sel_hi:[1,0,1]
	v_add_f32_dpp v34, v34, v34 row_ror:2 row_mask:0xf bank_mask:0xf bound_ctrl:1
	v_add_f32_dpp v36, v36, v36 row_ror:2 row_mask:0xf bank_mask:0xf bound_ctrl:1
	s_nop 0
	v_add_f32_dpp v34, v34, v34 row_ror:4 row_mask:0xf bank_mask:0xf bound_ctrl:1
	s_waitcnt lgkmcnt(7)
	s_nop 0
	s_nop 0
	v_add_f32_dpp v34, v34, v34 row_ror:8 row_mask:0xf bank_mask:0xf bound_ctrl:1
	v_pk_fma_f32 v[22:23], v[54:55], v[34:35], v[22:23] op_sel_hi:[1,0,1]
	v_pk_fma_f32 v[24:25], v[56:57], v[34:35], v[24:25] op_sel_hi:[1,0,1]
	s_waitcnt lgkmcnt(2)
; #define LAS __attribute__((address_space(3)))
; template <int CTRL> __device__ __forceinline__ float dpp_f(float x) { return __int_as_float(__builtin_amdgcn_update_dpp(0, __float_as_int(x), CTRL, 0xf, 0xf, false)); }
; __device__ __forceinline__ void p8_scan(const Args& a, LAS unsigned char* lds) {
;     ...
;             for (int c = 0; c < T / TC; ++c) {
;                 const int cur = c & 1;
;                 const LAS float* bt = buf + cur * TC * SPITCH;
;                 LAS float* yd = holds_y ? (ybuf + cur * TC * 64 + 4 * (4 * w + (lane >> 4)) + ((lane & 15) >> 2)) : (dump + lane);
;                 ScanOps o; scan_ld(o, bt, jq4, myrow);
; #pragma unroll 16
;                 for (int tt = 0; tt < TC; ++tt) {
;                     ScanOps n; scan_ld(n, bt + (tt + 1 < TC ? tt + 1 : tt) * SPITCH, jq4, myrow);
;                     __builtin_amdgcn_sched_barrier(0);
;                     f32x2 ta = S01 * o.al.lo, ty = S01 * o.wr.lo; ta = S23 * o.al.hi + ta; ty = S23 * o.wr.hi + ty;
;                     float pa = ta.x + ta.y, py = ty.x + ty.y;
;                     f32x2 kv01 = o.kv.lo * o.vi, kv23 = o.kv.hi * o.vi;
;     ...
;                     asm volatile("" : "+v"(kv01), "+v"(kv23), "+v"(vc));
;                     pa += dpp_f<0x121>(pa); py += dpp_f<0x121>(py); pa += dpp_f<0x122>(pa); py += dpp_f<0x122>(py);
;                     pa += dpp_f<0x124>(pa); pa += dpp_f<0x128>(pa);
;                     S01 = S01 * o.wv.lo + (o.be.lo * pa + kv01);
;                     S23 = S23 * o.wv.hi + (o.be.hi * pa + kv23);
;     ...
;                     __builtin_amdgcn_sched_barrier(0);
;                     o = n;
;                 }
;                 __syncthreads();
	v_pk_mul_f32 v[34:35], v[22:23], v[10:11]
	v_pk_mul_f32 v[66:67], v[22:23], v[58:59]
	v_pk_fma_f32 v[34:35], v[24:25], v[12:13], v[34:35]
	v_pk_fma_f32 v[66:67], v[24:25], v[60:61], v[66:67]
	ds_read_b128 v[50:53], v38 offset:45984
	ds_read_b128 v[46:49], v38 offset:45728
	ds_read_b32 v62, v39 offset:46752
	ds_read_b128 v[54:57], v38 offset:46240
	ds_read_b128 v[58:61], v38 offset:46496
	v_add_f32_e32 v34, v34, v35
	v_add_f32_e32 v66, v66, v67
	v_pk_fma_f32 v[22:23], v[6:7], v[28:29], v[22:23] op_sel_hi:[1,0,1]
	v_add_f32_dpp v34, v34, v34 row_ror:1 row_mask:0xf bank_mask:0xf bound_ctrl:1
	v_add_f32_dpp v66, v66, v66 row_ror:1 row_mask:0xf bank_mask:0xf bound_ctrl:1
	v_pk_fma_f32 v[24:25], v[8:9], v[28:29], v[24:25] op_sel_hi:[1,0,1]
	v_add_f32_dpp v34, v34, v34 row_ror:2 row_mask:0xf bank_mask:0xf bound_ctrl:1
	v_add_f32_dpp v66, v66, v66 row_ror:2 row_mask:0xf bank_mask:0xf bound_ctrl:1
	ds_write2st64_b32 v41, v36, v66 offset0:26 offset1:27
	v_add_f32_dpp v34, v34, v34 row_ror:4 row_mask:0xf bank_mask:0xf bound_ctrl:1
	s_waitcnt lgkmcnt(7)
	s_nop 0
	s_nop 0
	v_add_f32_dpp v34, v34, v34 row_ror:8 row_mask:0xf bank_mask:0xf bound_ctrl:1
	v_pk_fma_f32 v[22:23], v[14:15], v[34:35], v[22:23] op_sel_hi:[1,0,1]
	v_pk_fma_f32 v[24:25], v[16:17], v[34:35], v[24:25] op_sel_hi:[1,0,1]
	s_waitcnt lgkmcnt(3)
	v_pk_mul_f32 v[34:35], v[22:23], v[50:51]
	v_pk_mul_f32 v[36:37], v[22:23], v[18:19]
	v_pk_fma_f32 v[34:35], v[24:25], v[52:53], v[34:35]
	v_pk_fma_f32 v[36:37], v[24:25], v[20:21], v[36:37]
	ds_read_b128 v[10:13], v38 offset:47552
	ds_read_b128 v[6:9], v38 offset:47296
	ds_read_b32 v28, v39 offset:48320
	ds_read_b128 v[14:17], v38 offset:47808
	ds_read_b128 v[18:21], v38 offset:48064
	v_add_f32_e32 v34, v34, v35
	v_add_f32_e32 v36, v36, v37
	v_pk_fma_f32 v[22:23], v[46:47], v[62:63], v[22:23] op_sel_hi:[1,0,1]
	v_add_f32_dpp v34, v34, v34 row_ror:1 row_mask:0xf bank_mask:0xf bound_ctrl:1
	v_add_f32_dpp v36, v36, v36 row_ror:1 row_mask:0xf bank_mask:0xf bound_ctrl:1
	v_pk_fma_f32 v[24:25], v[48:49], v[62:63], v[24:25] op_sel_hi:[1,0,1]
	v_add_f32_dpp v34, v34, v34 row_ror:2 row_mask:0xf bank_mask:0xf bound_ctrl:1
	v_add_f32_dpp v36, v36, v36 row_ror:2 row_mask:0xf bank_mask:0xf bound_ctrl:1
	s_nop 0
	v_add_f32_dpp v34, v34, v34 row_ror:4 row_mask:0xf bank_mask:0xf bound_ctrl:1
	s_waitcnt lgkmcnt(7)
	s_nop 0
	s_nop 0
	v_add_f32_dpp v34, v34, v34 row_ror:8 row_mask:0xf bank_mask:0xf bound_ctrl:1
	v_pk_fma_f32 v[22:23], v[54:55], v[34:35], v[22:23] op_sel_hi:[1,0,1]
	v_pk_fma_f32 v[24:25], v[56:57], v[34:35], v[24:25] op_sel_hi:[1,0,1]
	s_waitcnt lgkmcnt(2)
	v_pk_mul_f32 v[34:35], v[22:23], v[10:11]
	v_pk_mul_f32 v[66:67], v[22:23], v[58:59]
	v_pk_fma_f32 v[34:35], v[24:25], v[12:13], v[34:35]
	v_pk_fma_f32 v[66:67], v[24:25], v[60:61], v[66:67]
	ds_read_b128 v[50:53], v38 offset:49120
	ds_read_b128 v[46:49], v38 offset:48864
	ds_read_b32 v62, v39 offset:49888
	ds_read_b128 v[42:45], v38 offset:48608
	ds_read_b128 v[54:57], v38 offset:49376
	ds_read_b128 v[58:61], v38 offset:49632
	v_add_f32_e32 v34, v34, v35
	v_add_f32_e32 v66, v66, v67
	v_pk_fma_f32 v[22:23], v[6:7], v[28:29], v[22:23] op_sel_hi:[1,0,1]
	v_add_f32_dpp v34, v34, v34 row_ror:1 row_mask:0xf bank_mask:0xf bound_ctrl:1
	v_add_f32_dpp v66, v66, v66 row_ror:1 row_mask:0xf bank_mask:0xf bound_ctrl:1
	v_pk_fma_f32 v[24:25], v[8:9], v[28:29], v[24:25] op_sel_hi:[1,0,1]
	v_add_f32_dpp v34, v34, v34 row_ror:2 row_mask:0xf bank_mask:0xf bound_ctrl:1
	v_add_f32_dpp v66, v66, v66 row_ror:2 row_mask:0xf bank_mask:0xf bound_ctrl:1
	ds_write2st64_b32 v41, v36, v66 offset0:28 offset1:29
	v_add_f32_dpp v34, v34, v34 row_ror:4 row_mask:0xf bank_mask:0xf bound_ctrl:1
	s_waitcnt lgkmcnt(8)
	s_nop 0
	s_nop 0
	v_add_f32_dpp v34, v34, v34 row_ror:8 row_mask:0xf bank_mask:0xf bound_ctrl:1
	v_pk_fma_f32 v[22:23], v[14:15], v[34:35], v[22:23] op_sel_hi:[1,0,1]
	v_pk_fma_f32 v[24:25], v[16:17], v[34:35], v[24:25] op_sel_hi:[1,0,1]
	s_waitcnt lgkmcnt(4)
	v_pk_mul_f32 v[34:35], v[22:23], v[50:51]
	v_pk_mul_f32 v[36:37], v[22:23], v[18:19]
	v_pk_fma_f32 v[34:35], v[24:25], v[52:53], v[34:35]
	v_pk_fma_f32 v[36:37], v[24:25], v[20:21], v[36:37]
	v_add_f32_e32 v34, v34, v35
	v_add_f32_e32 v36, v36, v37
	v_pk_fma_f32 v[22:23], v[46:47], v[62:63], v[22:23] op_sel_hi:[1,0,1]
	v_add_f32_dpp v34, v34, v34 row_ror:1 row_mask:0xf bank_mask:0xf bound_ctrl:1
	v_add_f32_dpp v36, v36, v36 row_ror:1 row_mask:0xf bank_mask:0xf bound_ctrl:1
	v_pk_fma_f32 v[24:25], v[48:49], v[62:63], v[24:25] op_sel_hi:[1,0,1]
	v_add_f32_dpp v34, v34, v34 row_ror:2 row_mask:0xf bank_mask:0xf bound_ctrl:1
	v_add_f32_dpp v36, v36, v36 row_ror:2 row_mask:0xf bank_mask:0xf bound_ctrl:1
	s_nop 0
	v_add_f32_dpp v34, v34, v34 row_ror:4 row_mask:0xf bank_mask:0xf bound_ctrl:1
	s_waitcnt lgkmcnt(0)
	s_nop 0
	s_nop 0
	v_add_f32_dpp v34, v34, v34 row_ror:8 row_mask:0xf bank_mask:0xf bound_ctrl:1
	v_pk_fma_f32 v[22:23], v[54:55], v[34:35], v[22:23] op_sel_hi:[1,0,1]
	v_pk_fma_f32 v[24:25], v[56:57], v[34:35], v[24:25] op_sel_hi:[1,0,1]
	v_pk_mul_f32 v[66:67], v[22:23], v[58:59]
	v_pk_fma_f32 v[66:67], v[24:25], v[60:61], v[66:67]
	v_add_f32_e32 v66, v66, v67
	v_pk_mul_f32 v[22:23], v[22:23], v[42:43]
	v_pk_mul_f32 v[24:25], v[24:25], v[44:45]
	v_add_f32_dpp v66, v66, v66 row_ror:1 row_mask:0xf bank_mask:0xf bound_ctrl:1
	s_nop 0
	s_nop 0
	v_add_f32_dpp v66, v66, v66 row_ror:2 row_mask:0xf bank_mask:0xf bound_ctrl:1
	ds_write2st64_b32 v41, v36, v66 offset0:30 offset1:31
	s_add_i32 s14, s14, 1
	s_cmpk_eq_i32 s14, 0x100
	s_waitcnt lgkmcnt(0)
	s_barrier
	s_cbranch_scc0 .LBB0_1090
	s_setprio 0
	s_mov_b64 s[44:45], 0
; __device__ __forceinline__ void scan_issue(ScanRegs& R, const bf16_t* PRKV, const unsigned short* WLOG, const bf16_t* ASIG, size_t tok, int ch, int want_prev) {
;     const bf16_t* pp = PRKV + tok * 3072 + ch;
;     R.pr = *(const u32x2*)pp; R.pk = *(const u32x2*)(pp + 1024); R.pv = *(const u32x2*)(pp + 2048);
;     R.qr = (u32x2){0u, 0u}; R.qk = (u32x2){0u, 0u}; R.qv = (u32x2){0u, 0u};
;     if (want_prev == 1) { R.qr = *(const u32x2*)(pp - 3072); R.qk = *(const u32x2*)(pp - 3072 + 1024); R.qv = *(const u32x2*)(pp - 3072 + 2048); }
;     R.wl = *(const u32x2*)(WLOG + tok * 1024 + ch); R.as = *(const u32x2*)(ASIG + tok * 1024 + ch);
; }
; __device__ __forceinline__ void p8_scan(const Args& a, LAS unsigned char* lds) {
;     ...
;         if (w >= 4) {
;             const f32x4 mur = *(const f32x4*)(mu_rkv + ch), muk = *(const f32x4*)(mu_rkv + 1024 + ch), muv = *(const f32x4*)(mu_rkv + 2048 + ch),
;                         kkc = *(const f32x4*)(k_k + ch), kac = *(const f32x4*)(k_a + ch), rkc = *(const f32x4*)(r_k + ch);
;             ScanRegs A0, A1, B0, B1;
;             { const size_t tok = (size_t)b * T + 2 * ltt; scan_issue(A0, PRKV, WLOG, ASIG, tok, ch, ltt > 0 ? 1 : 2); scan_issue(A1, PRKV, WLOG, ASIG, tok + 1, ch, 0);
;               const float b0 = scan_prepare(A0, A0.qr, A0.qk, A0.qv, buf + (2 * ltt) * SPITCH, cq, mur, muk, muv, kkc, kac, rkc);
;               const float b1 = scan_prepare(A1, A0.pr, A0.pk, A0.pv, buf + (2 * ltt + 1) * SPITCH, cq, mur, muk, muv, kkc, kac, rkc);
;               if (rq == 0 && cq == 0) { BONUS[tok * 16 + h] = b0; BONUS[(tok + 1) * 16 + h] = b1; }
;               scan_issue(A0, PRKV, WLOG, ASIG, tok + TC, ch, 1); scan_issue(A1, PRKV, WLOG, ASIG, tok + TC + 1, ch, 0);
;               scan_issue(B0, PRKV, WLOG, ASIG, tok + 2 * TC, ch, 1); scan_issue(B1, PRKV, WLOG, ASIG, tok + 2 * TC + 1, ch, 0); }
.LBB0_1094:
	s_and_b64 vcc, exec, s[44:45]
	s_cbranch_vccz .LBB0_1087
	v_mbcnt_lo_u32_b32 v233, -1, 0
	v_mbcnt_hi_u32_b32 v233, -1, v233
	v_cmp_lt_u32_e32 vcc, 15, v233
	v_cndmask_b32_e64 v235, 0, 1.0, vcc
	v_cmp_lt_u32_e32 vcc, 31, v233
	v_cndmask_b32_e64 v237, 0, 1.0, vcc
	v_sub_f32_e32 v236, 1.0, v235
	v_sub_f32_e32 v238, 1.0, v237
	v_add_u32_e32 v234, 32, v233
	v_add_u32_e32 v233, 48, v233
	v_and_b32_e32 v234, 63, v234
	v_and_b32_e32 v233, 63, v233
	v_lshlrev_b32_e32 v234, 2, v234
	v_lshlrev_b32_e32 v233, 2, v233
	s_and_b32 s14, s71, 15
	s_lshl_b32 s43, s71, 9
	s_lshl_b32 s88, s14, 6
	s_and_b32 s43, s43, 0x6000
	v_or_b32_e32 v1, s88, v27
	v_or_b32_e32 v139, s43, v125
	v_mov_b64_e32 v[32:33], s[0:1]
	s_movk_i32 s43, 0x1800
	s_waitcnt vmcnt(15)
	v_mad_u64_u32 v[34:35], s[44:45], v139, s43, v[32:33]
	v_lshlrev_b32_e32 v28, 1, v1
	s_mov_b64 s[56:57], s[84:85]
	v_readlane_b32 s72, v232, 16
	v_lshl_add_u64 v[32:33], v[34:35], 0, v[28:29]
	v_lshlrev_b32_e32 v22, 2, v1
	v_readlane_b32 s78, v232, 22
	v_readlane_b32 s79, v232, 23
	s_waitcnt vmcnt(12)
	v_add_co_u32_e32 v36, vcc, 0x1000, v32
	global_load_dwordx4 v[2:5], v22, s[20:21]
	global_load_dwordx4 v[6:9], v22, s[22:23]
	global_load_dwordx4 v[10:13], v22, s[54:55]
	v_readlane_b32 s80, v232, 24
	v_readlane_b32 s81, v232, 25
	v_readlane_b32 s82, v232, 26
	v_readlane_b32 s83, v232, 27
	global_load_dwordx4 v[14:17], v22, s[78:79]
	s_nop 1
	global_load_dwordx4 v[18:21], v22, s[80:81]
	s_nop 0
	global_load_dwordx4 v[22:25], v22, s[82:83]
	v_addc_co_u32_e32 v37, vcc, 0, v33, vcc
	global_load_dwordx2 v[40:41], v[32:33], off
	global_load_dwordx2 v[38:39], v[32:33], off offset:2048
	global_load_dwordx2 v[52:53], v[36:37], off
	s_waitcnt vmcnt(14)
	v_mov_b32_e32 v48, 0
	v_mov_b32_e32 v49, 0
	v_mov_b32_e32 v50, 0
	v_mov_b32_e32 v51, 0
	v_mov_b32_e32 v54, 0
	v_mov_b32_e32 v55, 0
	v_readlane_b32 s73, v232, 17
	v_readlane_b32 s74, v232, 18
	v_readlane_b32 s75, v232, 19
	v_readlane_b32 s76, v232, 20
	v_readlane_b32 s77, v232, 21
	v_readlane_b32 s84, v232, 28
	v_readlane_b32 s85, v232, 29
	v_readlane_b32 s86, v232, 30
	v_readlane_b32 s87, v232, 31
	s_and_saveexec_b64 s[44:45], s[6:7]
	s_cbranch_execz .LBB0_1097
	v_add_co_u32_e32 v36, vcc, 0xfffff000, v32
	s_nop 1
	v_addc_co_u32_e32 v37, vcc, -1, v33, vcc
	global_load_dwordx2 v[48:49], v[36:37], off offset:-2048
	global_load_dwordx2 v[50:51], v[32:33], off offset:-4096
	global_load_dwordx2 v[54:55], v[32:33], off offset:-2048
.LBB0_1097:
	s_or_b64 exec, exec, s[44:45]
	v_lshlrev_b32_e32 v32, 11, v139
	v_mov_b32_e32 v33, v29
	v_lshl_add_u64 v[42:43], s[90:91], 0, v[32:33]
	v_lshl_add_u64 v[42:43], v[42:43], 0, v[28:29]
	global_load_dwordx2 v[60:61], v[42:43], off
	v_lshl_add_u64 v[36:37], s[8:9], 0, v[32:33]
	v_lshl_add_u64 v[36:37], v[36:37], 0, v[28:29]
	s_mov_b64 s[44:45], 0x1800
	global_load_dwordx2 v[62:63], v[36:37], off
	v_or_b32_e32 v1, 1, v139
	s_waitcnt vmcnt(3)
	v_lshlrev_b32_e32 v46, 16, v38
	v_and_b32_e32 v47, 0xffff0000, v38
	s_waitcnt vmcnt(2)
	v_lshlrev_b32_e32 v36, 16, v52
	v_and_b32_e32 v37, 0xffff0000, v52
	v_lshlrev_b32_e32 v44, 16, v39
	v_and_b32_e32 v45, 0xffff0000, v39
	v_lshlrev_b32_e32 v38, 16, v53
	v_and_b32_e32 v39, 0xffff0000, v53
	v_lshlrev_b32_e32 v52, 16, v55
	v_and_b32_e32 v53, 0xffff0000, v55
	v_lshl_add_u64 v[34:35], v[34:35], 0, s[44:45]
	v_mov_b32_e32 v57, v29
	v_lshlrev_b32_e32 v58, 16, v54
	v_and_b32_e32 v59, 0xffff0000, v54
	v_lshlrev_b32_e32 v54, 16, v50
	v_and_b32_e32 v55, 0xffff0000, v50
	v_lshlrev_b32_e32 v50, 16, v51
	v_and_b32_e32 v51, 0xffff0000, v51
	s_movk_i32 s43, 0x1000
	v_lshlrev_b32_e32 v56, 11, v1
	v_pk_add_f32 v[52:53], v[52:53], v[38:39] neg_lo:[0,1] neg_hi:[0,1]
	v_lshl_add_u64 v[72:73], v[34:35], 0, v[28:29]
	v_lshlrev_b32_e32 v42, 16, v40
	v_and_b32_e32 v43, 0xffff0000, v40
	v_lshlrev_b32_e32 v64, 16, v48
	v_and_b32_e32 v65, 0xffff0000, v48
	v_pk_add_f32 v[70:71], v[50:51], v[44:45] neg_lo:[0,1] neg_hi:[0,1]
	v_lshl_add_u64 v[50:51], s[8:9], 0, v[56:57]
	v_lshl_add_u64 v[56:57], s[90:91], 0, v[56:57]
	v_pk_fma_f32 v[66:67], v[8:9], v[52:53], v[38:39]
	v_add_co_u32_e32 v52, vcc, s43, v72
	v_pk_add_f32 v[58:59], v[58:59], v[36:37] neg_lo:[0,1] neg_hi:[0,1]
	v_pk_add_f32 v[54:55], v[54:55], v[46:47] neg_lo:[0,1] neg_hi:[0,1]
	v_pk_add_f32 v[68:69], v[64:65], v[42:43] neg_lo:[0,1] neg_hi:[0,1]
	v_addc_co_u32_e32 v53, vcc, 0, v73, vcc
	v_lshl_add_u64 v[56:57], v[56:57], 0, v[28:29]
	v_pk_fma_f32 v[64:65], v[6:7], v[58:59], v[36:37]
	v_pk_fma_f32 v[74:75], v[2:3], v[54:55], v[46:47]
	v_pk_fma_f32 v[84:85], v[10:11], v[68:69], v[42:43]
	v_lshl_add_u64 v[68:69], v[50:51], 0, v[28:29]
	global_load_dwordx2 v[50:51], v[72:73], off
	global_load_dwordx2 v[54:55], v[72:73], off offset:2048
	global_load_dwordx2 v[58:59], v[52:53], off
	s_nop 0
	global_load_dwordx2 v[52:53], v[68:69], off
	s_nop 0
	global_load_dwordx2 v[56:57], v[56:57], off
	v_pk_fma_f32 v[70:71], v[4:5], v[70:71], v[44:45]
	v_pk_mul_f32 v[76:77], v[14:15], v[74:75]
	v_pk_mul_f32 v[78:79], v[16:17], v[70:71]
	v_pk_mul_f32 v[68:69], v[76:77], v[76:77]
	v_pk_mul_f32 v[72:73], v[78:79], v[78:79]
	v_add_f32_e32 v33, v68, v69
	v_add_f32_e32 v33, v72, v33
	v_add_f32_e32 v33, v73, v33
	v_lshlrev_b32_e32 v40, 16, v41
	v_and_b32_e32 v41, 0xffff0000, v41
	v_add_f32_dpp v33, v33, v33 row_ror:1 row_mask:0xf bank_mask:0xf bound_ctrl:1
	s_waitcnt vmcnt(6)
; #define LAS __attribute__((address_space(3)))
; __device__ __forceinline__ float scan_prepare(const ScanRegs& R, const u32x2 qr_, const u32x2 qk_, const u32x2 qv_, LAS float* slot, int cq, const f32x4 mur, const f32x4 muk, const f32x4 muv, const f32x4 kkc, const f32x4 kac, const f32x4 rkc) {
;     float pr[4], pk[4], pv[4], qr[4], qk[4], qv[4], av[4], om[4];
;     unpack4(R.pr, pr); unpack4(R.pk, pk); unpack4(R.pv, pv); unpack4(qr_, qr); unpack4(qk_, qk); unpack4(qv_, qv); unpack4(R.as, av);
;     om[0] = f16_to_f((unsigned short)(R.wl.x & 0xffffu)); om[1] = f16_to_f((unsigned short)(R.wl.x >> 16)); om[2] = f16_to_f((unsigned short)(R.wl.y & 0xffffu)); om[3] = f16_to_f((unsigned short)(R.wl.y >> 16));
;     float rr[4], vv[4], kn[4], k2[4], dec[4], bu[4];
;     float ssq = 0.f, bon = 0.f, c1 = 0.f, c2 = 0.f;
; #pragma unroll
;     for (int j = 0; j < 4; ++j) {
;         rr[j] = pr[j] + (qr[j] - pr[j]) * mur[j]; const float kk0 = pk[j] + (qk[j] - pk[j]) * muk[j]; vv[j] = pv[j] + (qv[j] - pv[j]) * muv[j];
;         dec[j] = 1.0f - om[j];
;         kn[j] = kk0 * kkc[j]; ssq += kn[j] * kn[j];
;         k2[j] = kk0 * (1.0f + (av[j] - 1.0f) * kac[j]);
;         const float t = rr[j] * k2[j]; bon += t * rkc[j]; c2 += t;
;         bu[j] = kn[j] * av[j]; c1 += bu[j] * rr[j];
;     }
;     ssq += dpp_f<0x121>(ssq); bon += dpp_f<0x121>(bon); c1 += dpp_f<0x121>(c1); c2 += dpp_f<0x121>(c2);
;     ssq += dpp_f<0x122>(ssq); bon += dpp_f<0x122>(bon); c1 += dpp_f<0x122>(c1); c2 += dpp_f<0x122>(c2);
;     ssq += dpp_f<0x124>(ssq); bon += dpp_f<0x124>(bon); c1 += dpp_f<0x124>(c1); c2 += dpp_f<0x124>(c2);
;     ssq += dpp_f<0x128>(ssq); bon += dpp_f<0x128>(bon); c1 += dpp_f<0x128>(c1); c2 += dpp_f<0x128>(c2);
;     const float inv = __builtin_amdgcn_rsqf(fmaxf(ssq, 1e-24f));
;     f32x4 o_al, o_be, o_wr;
; #pragma unroll
;     for (int j = 0; j < 4; ++j) { o_al[j] = -(kn[j] * inv); o_be[j] = bu[j] * inv; o_wr[j] = dec[j] * rr[j]; }
;     LAS f32x4* s4 = (LAS f32x4*)slot;
;     s4[cq] = (f32x4){dec[0], dec[1], dec[2], dec[3]}; s4[16 + cq] = (f32x4){k2[0], k2[1], k2[2], k2[3]}; s4[32 + cq] = o_al; s4[48 + cq] = o_be; s4[64 + cq] = o_wr;
;     s4[80 + cq] = (f32x4){vv[0], vv[1], vv[2], vv[3]};
;     if (cq == 0) *(LAS f32x2*)(slot + 384) = (f32x2){c1 * inv, c2};
;     return bon;
; }
	v_lshlrev_b32_e32 v68, 16, v60
	v_and_b32_e32 v69, 0xffff0000, v60
	v_pk_add_f32 v[80:81], v[68:69], -1.0 op_sel_hi:[1,0]
	v_add_f32_dpp v33, v33, v33 row_ror:2 row_mask:0xf bank_mask:0xf bound_ctrl:1
	v_pk_mul_f32 v[86:87], v[76:77], v[68:69]
	v_pk_fma_f32 v[68:69], v[18:19], v[80:81], 1.0 op_sel_hi:[1,1,0]
	v_add_f32_dpp v33, v33, v33 row_ror:4 row_mask:0xf bank_mask:0xf bound_ctrl:1
	v_pk_mul_f32 v[80:81], v[84:85], v[86:87]
	v_pk_mul_f32 v[68:69], v[74:75], v[68:69]
	v_add_f32_dpp v33, v33, v33 row_ror:8 row_mask:0xf bank_mask:0xf bound_ctrl:1
	v_add_f32_e32 v48, 0, v80
	v_pk_mul_f32 v[74:75], v[84:85], v[68:69]
	v_max_f32_e32 v33, 0x179abe15, v33
	v_lshlrev_b32_e32 v60, 16, v61
	v_and_b32_e32 v61, 0xffff0000, v61
	v_add_f32_e32 v90, v81, v48
	v_add_f32_e32 v48, 0, v74
	v_pk_add_f32 v[82:83], v[60:61], -1.0 op_sel_hi:[1,0]
	v_fma_f32 v91, v22, v74, 0
	v_add_f32_e32 v92, v75, v48
	v_rsq_f32_e32 v48, v33
	v_fmac_f32_e32 v91, v23, v75
	v_pk_fma_f32 v[74:75], v[20:21], v[82:83], 1.0 op_sel_hi:[1,1,0]
	v_pk_mul_f32 v[60:61], v[78:79], v[60:61]
	v_pk_mul_f32 v[70:71], v[70:71], v[74:75]
	v_lshlrev_b32_e32 v74, 16, v49
	v_and_b32_e32 v75, 0xffff0000, v49
	v_pk_add_f32 v[74:75], v[74:75], v[40:41] neg_lo:[0,1] neg_hi:[0,1]
	v_pk_mul_f32 v[80:81], v[86:87], v[48:49] op_sel_hi:[1,0]
	v_pk_fma_f32 v[86:87], v[12:13], v[74:75], v[40:41]
	s_waitcnt vmcnt(5)
	v_cvt_f32_f16_e32 v72, v62
	v_cvt_f32_f16_sdwa v73, v62 dst_sel:DWORD dst_unused:UNUSED_PAD src0_sel:WORD_1
	v_pk_mul_f32 v[82:83], v[60:61], v[48:49] op_sel_hi:[1,0]
	v_cvt_f32_f16_e32 v62, v63
	v_cvt_f32_f16_sdwa v63, v63 dst_sel:DWORD dst_unused:UNUSED_PAD src0_sel:WORD_1
	v_pk_mul_f32 v[88:89], v[86:87], v[70:71]
	v_pk_mul_f32 v[60:61], v[86:87], v[60:61]
	v_pk_mul_f32 v[78:79], v[78:79], v[48:49] op_sel_hi:[1,0] neg_lo:[0,1] neg_hi:[0,1]
	v_pk_mul_f32 v[76:77], v[76:77], v[48:49] op_sel_hi:[1,0] neg_lo:[0,1] neg_hi:[0,1]
	v_fmac_f32_e32 v91, v24, v88
	v_add_f32_e32 v33, v88, v92
	v_add_f32_e32 v49, v60, v90
	v_fmac_f32_e32 v91, v25, v89
	v_add_f32_e32 v33, v89, v33
	v_add_f32_e32 v49, v61, v49
	v_add_f32_dpp v60, v91, v91 row_ror:1 row_mask:0xf bank_mask:0xf bound_ctrl:1
	v_add_f32_dpp v33, v33, v33 row_ror:1 row_mask:0xf bank_mask:0xf bound_ctrl:1
	v_add_f32_dpp v49, v49, v49 row_ror:1 row_mask:0xf bank_mask:0xf bound_ctrl:1
	v_pk_add_f32 v[74:75], v[62:63], 1.0 op_sel_hi:[1,0] neg_lo:[1,0] neg_hi:[1,0]
	v_add_f32_dpp v60, v60, v60 row_ror:2 row_mask:0xf bank_mask:0xf bound_ctrl:1
	v_add_f32_dpp v49, v49, v49 row_ror:2 row_mask:0xf bank_mask:0xf bound_ctrl:1
	v_add_f32_dpp v62, v33, v33 row_ror:2 row_mask:0xf bank_mask:0xf bound_ctrl:1
	v_add_f32_dpp v33, v60, v60 row_ror:4 row_mask:0xf bank_mask:0xf bound_ctrl:1
	v_add_f32_dpp v61, v49, v49 row_ror:4 row_mask:0xf bank_mask:0xf bound_ctrl:1
	v_add_f32_dpp v60, v62, v62 row_ror:4 row_mask:0xf bank_mask:0xf bound_ctrl:1
	v_mov_b32_e32 v62, v29
	v_mov_b32_e32 v63, v29
	v_mov_b32_e32 v49, v29
	v_pk_add_f32 v[72:73], v[72:73], 1.0 op_sel_hi:[1,0] neg_lo:[1,0] neg_hi:[1,0]
	v_mov_b32_dpp v62, v61 row_ror:8 row_mask:0xf bank_mask:0xf
	v_mov_b32_dpp v63, v60 row_ror:8 row_mask:0xf bank_mask:0xf
	v_mov_b32_dpp v49, v33 row_ror:8 row_mask:0xf bank_mask:0xf
	v_pk_mul_f32 v[84:85], v[84:85], 1.0 op_sel_hi:[1,0]
	v_pk_mul_f32 v[86:87], v[86:87], 1.0 op_sel_hi:[1,0]
	v_mov_b32_e32 v174, v72
	v_mov_b32_e32 v175, v73
	v_mov_b32_e32 v176, v74
	v_mov_b32_e32 v177, v75
	v_mov_b32_e32 v178, v68
	v_mov_b32_e32 v179, v69
	v_mov_b32_e32 v180, v70
	v_mov_b32_e32 v181, v71
	v_mov_b32_e32 v182, v76
	v_mov_b32_e32 v183, v77
	v_mov_b32_e32 v184, v78
	v_mov_b32_e32 v185, v79
	v_mov_b32_e32 v186, v80
	v_mov_b32_e32 v187, v81
	v_mov_b32_e32 v188, v82
	v_mov_b32_e32 v189, v83
	v_mov_b32_e32 v190, v84
	v_mov_b32_e32 v191, v85
	v_mov_b32_e32 v192, v86
	v_mov_b32_e32 v193, v87
	v_mov_b32_e32 v194, v127
	ds_write_b128 v127, v[64:67] offset:1280
	s_nop 7
	s_nop 7
	s_and_saveexec_b64 s[44:45], s[4:5]
	v_add_f32_e32 v61, v61, v62
	v_mul_f32_e32 v62, v61, v48
	v_add_f32_e32 v63, v60, v63
	ds_write_b64 v126, v[62:63] offset:1536
	s_or_b64 exec, exec, s[44:45]
	s_waitcnt vmcnt(2)
	v_lshlrev_b32_e32 v70, 16, v58
	v_and_b32_e32 v71, 0xffff0000, v58
	v_lshlrev_b32_e32 v72, 16, v59
	v_and_b32_e32 v73, 0xffff0000, v59
	v_lshlrev_b32_e32 v58, 16, v54
	v_and_b32_e32 v59, 0xffff0000, v54
	v_pk_add_f32 v[46:47], v[46:47], v[58:59] neg_lo:[0,1] neg_hi:[0,1]
	s_waitcnt vmcnt(0)
; #define LAS __attribute__((address_space(3)))
; __device__ __forceinline__ float scan_prepare(const ScanRegs& R, const u32x2 qr_, const u32x2 qk_, const u32x2 qv_, LAS float* slot, int cq, const f32x4 mur, const f32x4 muk, const f32x4 muv, const f32x4 kkc, const f32x4 kac, const f32x4 rkc) {
;     float pr[4], pk[4], pv[4], qr[4], qk[4], qv[4], av[4], om[4];
;     unpack4(R.pr, pr); unpack4(R.pk, pk); unpack4(R.pv, pv); unpack4(qr_, qr); unpack4(qk_, qk); unpack4(qv_, qv); unpack4(R.as, av);
;     om[0] = f16_to_f((unsigned short)(R.wl.x & 0xffffu)); om[1] = f16_to_f((unsigned short)(R.wl.x >> 16)); om[2] = f16_to_f((unsigned short)(R.wl.y & 0xffffu)); om[3] = f16_to_f((unsigned short)(R.wl.y >> 16));
;     float rr[4], vv[4], kn[4], k2[4], dec[4], bu[4];
;     float ssq = 0.f, bon = 0.f, c1 = 0.f, c2 = 0.f;
; #pragma unroll
;     for (int j = 0; j < 4; ++j) {
;         rr[j] = pr[j] + (qr[j] - pr[j]) * mur[j]; const float kk0 = pk[j] + (qk[j] - pk[j]) * muk[j]; vv[j] = pv[j] + (qv[j] - pv[j]) * muv[j];
;         dec[j] = 1.0f - om[j];
;         kn[j] = kk0 * kkc[j]; ssq += kn[j] * kn[j];
;         k2[j] = kk0 * (1.0f + (av[j] - 1.0f) * kac[j]);
;         const float t = rr[j] * k2[j]; bon += t * rkc[j]; c2 += t;
;         bu[j] = kn[j] * av[j]; c1 += bu[j] * rr[j];
;     }
;     ssq += dpp_f<0x121>(ssq); bon += dpp_f<0x121>(bon); c1 += dpp_f<0x121>(c1); c2 += dpp_f<0x121>(c2);
;     ssq += dpp_f<0x122>(ssq); bon += dpp_f<0x122>(bon); c1 += dpp_f<0x122>(c1); c2 += dpp_f<0x122>(c2);
;     ssq += dpp_f<0x124>(ssq); bon += dpp_f<0x124>(bon); c1 += dpp_f<0x124>(c1); c2 += dpp_f<0x124>(c2);
;     ssq += dpp_f<0x128>(ssq); bon += dpp_f<0x128>(bon); c1 += dpp_f<0x128>(c1); c2 += dpp_f<0x128>(c2);
;     const float inv = __builtin_amdgcn_rsqf(fmaxf(ssq, 1e-24f));
;     f32x4 o_al, o_be, o_wr;
; #pragma unroll
;     for (int j = 0; j < 4; ++j) { o_al[j] = -(kn[j] * inv); o_be[j] = bu[j] * inv; o_wr[j] = dec[j] * rr[j]; }
;     LAS f32x4* s4 = (LAS f32x4*)slot;
;     s4[cq] = (f32x4){dec[0], dec[1], dec[2], dec[3]}; s4[16 + cq] = (f32x4){k2[0], k2[1], k2[2], k2[3]}; s4[32 + cq] = o_al; s4[48 + cq] = o_be; s4[64 + cq] = o_wr;
;     s4[80 + cq] = (f32x4){vv[0], vv[1], vv[2], vv[3]};
;     if (cq == 0) *(LAS f32x2*)(slot + 384) = (f32x2){c1 * inv, c2};
;     return bon;
; }
	v_lshlrev_b32_e32 v60, 16, v56
	v_pk_fma_f32 v[46:47], v[2:3], v[46:47], v[58:59]
	v_and_b32_e32 v61, 0xffff0000, v56
	v_pk_mul_f32 v[64:65], v[14:15], v[46:47]
	v_pk_add_f32 v[58:59], v[60:61], -1.0 op_sel_hi:[1,0]
	v_pk_mul_f32 v[74:75], v[64:65], v[60:61]
	v_lshlrev_b32_e32 v60, 16, v50
	v_and_b32_e32 v61, 0xffff0000, v50
	v_pk_fma_f32 v[58:59], v[18:19], v[58:59], 1.0 op_sel_hi:[1,1,0]
	v_pk_add_f32 v[42:43], v[42:43], v[60:61] neg_lo:[0,1] neg_hi:[0,1]
	v_pk_mul_f32 v[58:59], v[46:47], v[58:59]
	v_pk_fma_f32 v[76:77], v[10:11], v[42:43], v[60:61]
	v_pk_mul_f32 v[66:67], v[64:65], v[64:65]
	v_pk_mul_f32 v[42:43], v[76:77], v[58:59]
	v_cvt_f32_f16_sdwa v47, v52 dst_sel:DWORD dst_unused:UNUSED_PAD src0_sel:WORD_1
	v_fma_f32 v48, v22, v42, 0
	v_add_f32_e32 v42, 0, v42
	v_fmac_f32_e32 v48, v23, v43
	v_add_f32_e32 v78, v43, v42
	v_lshlrev_b32_e32 v42, 16, v55
	v_and_b32_e32 v43, 0xffff0000, v55
	v_pk_add_f32 v[44:45], v[44:45], v[42:43] neg_lo:[0,1] neg_hi:[0,1]
	v_cvt_f32_f16_e32 v46, v52
	v_pk_fma_f32 v[44:45], v[4:5], v[44:45], v[42:43]
	v_add_f32_e32 v50, v66, v67
	v_pk_mul_f32 v[54:55], v[16:17], v[44:45]
	v_pk_add_f32 v[62:63], v[46:47], 1.0 op_sel_hi:[1,0] neg_lo:[1,0] neg_hi:[1,0]
	v_pk_mul_f32 v[42:43], v[54:55], v[54:55]
	v_pk_mul_f32 v[46:47], v[76:77], v[74:75]
	v_add_f32_e32 v42, v42, v50
	v_add_f32_e32 v42, v43, v42
	v_add_f32_e32 v46, 0, v46
	v_add_f32_e32 v79, v47, v46
	v_add_f32_dpp v42, v42, v42 row_ror:1 row_mask:0xf bank_mask:0xf bound_ctrl:1
	v_lshlrev_b32_e32 v46, 16, v57
	v_and_b32_e32 v47, 0xffff0000, v57
	v_add_f32_dpp v42, v42, v42 row_ror:2 row_mask:0xf bank_mask:0xf bound_ctrl:1
	v_pk_add_f32 v[56:57], v[46:47], -1.0 op_sel_hi:[1,0]
	v_cvt_f32_f16_e32 v50, v53
	v_add_f32_dpp v42, v42, v42 row_ror:4 row_mask:0xf bank_mask:0xf bound_ctrl:1
	v_pk_fma_f32 v[56:57], v[20:21], v[56:57], 1.0 op_sel_hi:[1,1,0]
	v_pk_add_f32 v[36:37], v[36:37], v[70:71] neg_lo:[0,1] neg_hi:[0,1]
	v_add_f32_dpp v42, v42, v42 row_ror:8 row_mask:0xf bank_mask:0xf bound_ctrl:1
	v_max_f32_e32 v42, 0x179abe15, v42
	v_rsq_f32_e32 v42, v42
	v_pk_mul_f32 v[60:61], v[44:45], v[56:57]
	v_pk_mul_f32 v[44:45], v[54:55], v[46:47]
	v_lshlrev_b32_e32 v46, 16, v51
	v_and_b32_e32 v47, 0xffff0000, v51
	v_pk_add_f32 v[40:41], v[40:41], v[46:47] neg_lo:[0,1] neg_hi:[0,1]
	v_cvt_f32_f16_sdwa v51, v53 dst_sel:DWORD dst_unused:UNUSED_PAD src0_sel:WORD_1
	v_pk_fma_f32 v[52:53], v[12:13], v[40:41], v[46:47]
	v_pk_mul_f32 v[68:69], v[44:45], v[42:43] op_sel_hi:[1,0]
	v_pk_mul_f32 v[40:41], v[52:53], v[60:61]
	v_pk_mul_f32 v[44:45], v[52:53], v[44:45]
	v_pk_mul_f32 v[56:57], v[54:55], v[42:43] op_sel_hi:[1,0] neg_lo:[0,1] neg_hi:[0,1]
	v_pk_mul_f32 v[54:55], v[64:65], v[42:43] op_sel_hi:[1,0] neg_lo:[0,1] neg_hi:[0,1]
	v_pk_mul_f32 v[66:67], v[74:75], v[42:43] op_sel_hi:[1,0]
	v_fmac_f32_e32 v48, v24, v40
	v_add_f32_e32 v40, v40, v78
	v_add_f32_e32 v43, v44, v79
	v_fmac_f32_e32 v48, v25, v41
	v_add_f32_e32 v40, v41, v40
	v_add_f32_e32 v41, v45, v43
	v_add_f32_dpp v43, v48, v48 row_ror:1 row_mask:0xf bank_mask:0xf bound_ctrl:1
	v_add_f32_dpp v40, v40, v40 row_ror:1 row_mask:0xf bank_mask:0xf bound_ctrl:1
	v_add_f32_dpp v41, v41, v41 row_ror:1 row_mask:0xf bank_mask:0xf bound_ctrl:1
	v_add_f32_dpp v43, v43, v43 row_ror:2 row_mask:0xf bank_mask:0xf bound_ctrl:1
	v_add_f32_dpp v45, v40, v40 row_ror:2 row_mask:0xf bank_mask:0xf bound_ctrl:1
	v_add_f32_dpp v41, v41, v41 row_ror:2 row_mask:0xf bank_mask:0xf bound_ctrl:1
	v_add_f32_dpp v40, v43, v43 row_ror:4 row_mask:0xf bank_mask:0xf bound_ctrl:1
	v_add_f32_dpp v43, v45, v45 row_ror:4 row_mask:0xf bank_mask:0xf bound_ctrl:1
	v_add_f32_dpp v44, v41, v41 row_ror:4 row_mask:0xf bank_mask:0xf bound_ctrl:1
	v_mov_b32_e32 v45, v29
	v_mov_b32_e32 v46, v29
	v_mov_b32_e32 v41, v29
	v_pk_add_f32 v[38:39], v[38:39], v[72:73] neg_lo:[0,1] neg_hi:[0,1]
	v_pk_add_f32 v[64:65], v[50:51], 1.0 op_sel_hi:[1,0] neg_lo:[1,0] neg_hi:[1,0]
	v_mov_b32_dpp v45, v44 row_ror:8 row_mask:0xf bank_mask:0xf
	v_mov_b32_dpp v46, v43 row_ror:8 row_mask:0xf bank_mask:0xf
	v_mov_b32_dpp v41, v40 row_ror:8 row_mask:0xf bank_mask:0xf
	v_pk_fma_f32 v[38:39], v[8:9], v[38:39], v[72:73]
	v_pk_fma_f32 v[36:37], v[6:7], v[36:37], v[70:71]
	v_pk_mul_f32 v[50:51], v[76:77], 1.0 op_sel_hi:[1,0]
	v_pk_mul_f32 v[52:53], v[52:53], 1.0 op_sel_hi:[1,0]
	ds_write_b128 v129, v[36:39] offset:1280
	v_pk_mul_f32 v[196:197], v[174:175], v[62:63]
	v_pk_mul_f32 v[198:199], v[176:177], v[64:65]
	ds_bpermute_b32 v200, v233, v196
	ds_bpermute_b32 v201, v233, v197
	ds_bpermute_b32 v202, v233, v198
	ds_bpermute_b32 v203, v233, v199
	s_waitcnt lgkmcnt(0)
; #define LAS __attribute__((address_space(3)))
; __device__ __forceinline__ float scan_prepare(const ScanRegs& R, const u32x2 qr_, const u32x2 qk_, const u32x2 qv_, LAS float* slot, int cq, const f32x4 mur, const f32x4 muk, const f32x4 muv, const f32x4 kkc, const f32x4 kac, const f32x4 rkc) {
;     ...
;     const float inv = __builtin_amdgcn_rsqf(fmaxf(ssq, 1e-24f));
;     f32x4 o_al, o_be, o_wr;
; #pragma unroll
;     for (int j = 0; j < 4; ++j) { o_al[j] = -(kn[j] * inv); o_be[j] = bu[j] * inv; o_wr[j] = dec[j] * rr[j]; }
;     LAS f32x4* s4 = (LAS f32x4*)slot;
;     s4[cq] = (f32x4){dec[0], dec[1], dec[2], dec[3]}; s4[16 + cq] = (f32x4){k2[0], k2[1], k2[2], k2[3]}; s4[32 + cq] = o_al; s4[48 + cq] = o_be; s4[64 + cq] = o_wr;
;     s4[80 + cq] = (f32x4){vv[0], vv[1], vv[2], vv[3]};
;     if (cq == 0) *(LAS f32x2*)(slot + 384) = (f32x2){c1 * inv, c2};
;     return bon;
; }
; __device__ __forceinline__ void p8_scan(const Args& a, LAS unsigned char* lds) {
;     ...
;               if (rq == 0 && cq == 0) { BONUS[tok * 16 + h] = b0; BONUS[(tok + 1) * 16 + h] = b1; }
	v_fma_f32 v200, v200, v235, v236
	v_fma_f32 v201, v201, v235, v236
	v_fma_f32 v202, v202, v235, v236
	v_fma_f32 v203, v203, v235, v236
	v_pk_mul_f32 v[204:205], v[196:197], v[200:201]
	v_pk_mul_f32 v[206:207], v[198:199], v[202:203]
	ds_bpermute_b32 v208, v234, v204
	ds_bpermute_b32 v209, v234, v205
	ds_bpermute_b32 v210, v234, v206
	ds_bpermute_b32 v211, v234, v207
	s_waitcnt lgkmcnt(0)
	v_fma_f32 v208, v208, v237, v238
	v_fma_f32 v209, v209, v237, v238
	v_fma_f32 v210, v210, v237, v238
	v_fma_f32 v211, v211, v237, v238
	v_pk_mul_f32 v[212:213], v[200:201], v[208:209]
	v_pk_mul_f32 v[214:215], v[202:203], v[210:211]
	v_pk_mul_f32 v[216:217], v[212:213], v[174:175]
	v_pk_mul_f32 v[218:219], v[214:215], v[176:177]
	v_pk_mul_f32 v[220:221], v[216:217], v[62:63]
	v_pk_mul_f32 v[222:223], v[218:219], v[64:65]
	v_rcp_f32_e32 v224, v216
	v_rcp_f32_e32 v225, v217
	v_rcp_f32_e32 v226, v218
	v_rcp_f32_e32 v227, v219
	v_rcp_f32_e32 v228, v220
	v_rcp_f32_e32 v229, v221
	v_rcp_f32_e32 v230, v222
	v_rcp_f32_e32 v231, v223
	s_nop 0
	v_pk_mul_f32 v[182:183], v[182:183], v[212:213]
	v_pk_mul_f32 v[184:185], v[184:185], v[214:215]
	v_pk_mul_f32 v[178:179], v[178:179], v[224:225]
	v_pk_mul_f32 v[180:181], v[180:181], v[226:227]
	ds_write_b128 v194, v[178:181] offset:256
	s_nop 7
	s_nop 7
	v_pk_mul_f32 v[186:187], v[186:187], v[224:225]
	v_pk_mul_f32 v[188:189], v[188:189], v[226:227]
	ds_write_b128 v194, v[182:185] offset:512
	s_nop 7
	s_nop 7
	v_pk_mul_f32 v[190:191], v[190:191], v[216:217]
	v_pk_mul_f32 v[192:193], v[192:193], v[218:219]
	ds_write_b128 v194, v[186:189] offset:768
	s_nop 7
	s_nop 7
	v_pk_mul_f32 v[240:241], v[58:59], v[228:229]
	v_pk_mul_f32 v[242:243], v[60:61], v[230:231]
	ds_write_b128 v194, v[190:193] offset:1024
	s_nop 7
	s_nop 7
	v_pk_mul_f32 v[244:245], v[54:55], v[216:217]
	v_pk_mul_f32 v[246:247], v[56:57], v[218:219]
	ds_write_b128 v129, v[220:223]
	s_nop 7
	s_nop 7
	v_pk_mul_f32 v[196:197], v[66:67], v[228:229]
	v_pk_mul_f32 v[198:199], v[68:69], v[230:231]
	ds_write_b128 v129, v[240:243] offset:256
	s_nop 7
	s_nop 7
	v_pk_mul_f32 v[200:201], v[50:51], v[220:221]
	v_pk_mul_f32 v[202:203], v[52:53], v[222:223]
	ds_write_b128 v129, v[244:247] offset:512
	s_nop 7
	s_nop 7
	ds_write_b128 v129, v[196:199] offset:768
	s_nop 7
	s_nop 7
	ds_write_b128 v129, v[200:203] offset:1024
	s_nop 7
	s_nop 7
	s_and_saveexec_b64 s[44:45], s[4:5]
	s_mov_b64 s[84:85], s[56:57]
	v_add_f32_e32 v36, v44, v45
	v_mul_f32_e32 v36, v36, v42
	v_add_f32_e32 v37, v43, v46
	ds_write_b64 v128, v[36:37] offset:1536
	s_or_b64 exec, exec, s[44:45]
	s_cmp_lt_u32 s71, 64
	s_cselect_b64 s[44:45], -1, 0
	s_and_b64 s[44:45], s[4:5], s[44:45]
	s_xor_b64 s[52:53], s[44:45], -1
	v_mov_b64_e32 v[100:101], s[14:15]
	s_and_saveexec_b64 s[56:57], s[52:53]
	s_xor_b64 s[52:53], exec, s[56:57]
	v_mov_b64_e32 v[100:101], s[14:15]
	s_andn2_saveexec_b64 s[52:53], s[52:53]
	s_cbranch_execz .LBB0_1105
	v_lshlrev_b32_e32 v38, 6, v139
	v_mov_b32_e32 v39, v29
	v_lshlrev_b32_e32 v36, 6, v1
	v_mov_b32_e32 v37, v29
	s_lshl_b32 s14, s14, 2
	v_lshl_add_u64 v[38:39], s[12:13], 0, v[38:39]
	v_add_f32_e32 v33, v33, v49
	v_lshl_add_u64 v[36:37], s[12:13], 0, v[36:37]
	v_lshl_add_u64 v[38:39], v[38:39], 0, s[14:15]
	v_lshl_add_u64 v[36:37], v[36:37], 0, s[14:15]
	v_add_f32_e32 v1, v40, v41
	global_store_dword v[38:39], v33, off
	global_store_dword v[36:37], v1, off

; #define LAS __attribute__((address_space(3)))
; __device__ __forceinline__ float scan_prepare(const ScanRegs& R, const u32x2 qr_, const u32x2 qk_, const u32x2 qv_, LAS float* slot, int cq, const f32x4 mur, const f32x4 muk, const f32x4 muv, const f32x4 kkc, const f32x4 kac, const f32x4 rkc) {
;     float pr[4], pk[4], pv[4], qr[4], qk[4], qv[4], av[4], om[4];
;     unpack4(R.pr, pr); unpack4(R.pk, pk); unpack4(R.pv, pv); unpack4(qr_, qr); unpack4(qk_, qk); unpack4(qv_, qv); unpack4(R.as, av);
;     om[0] = f16_to_f((unsigned short)(R.wl.x & 0xffffu)); om[1] = f16_to_f((unsigned short)(R.wl.x >> 16)); om[2] = f16_to_f((unsigned short)(R.wl.y & 0xffffu)); om[3] = f16_to_f((unsigned short)(R.wl.y >> 16));
;     float rr[4], vv[4], kn[4], k2[4], dec[4], bu[4];
;     float ssq = 0.f, bon = 0.f, c1 = 0.f, c2 = 0.f;
; #pragma unroll
;     for (int j = 0; j < 4; ++j) {
;         rr[j] = pr[j] + (qr[j] - pr[j]) * mur[j]; const float kk0 = pk[j] + (qk[j] - pk[j]) * muk[j]; vv[j] = pv[j] + (qv[j] - pv[j]) * muv[j];
;         dec[j] = 1.0f - om[j];
;         kn[j] = kk0 * kkc[j]; ssq += kn[j] * kn[j];
;         k2[j] = kk0 * (1.0f + (av[j] - 1.0f) * kac[j]);
;         const float t = rr[j] * k2[j]; bon += t * rkc[j]; c2 += t;
;         bu[j] = kn[j] * av[j]; c1 += bu[j] * rr[j];
;     }
;     ssq += dpp_f<0x121>(ssq); bon += dpp_f<0x121>(bon); c1 += dpp_f<0x121>(c1); c2 += dpp_f<0x121>(c2);
;     ssq += dpp_f<0x122>(ssq); bon += dpp_f<0x122>(bon); c1 += dpp_f<0x122>(c1); c2 += dpp_f<0x122>(c2);
;     ssq += dpp_f<0x124>(ssq); bon += dpp_f<0x124>(bon); c1 += dpp_f<0x124>(c1); c2 += dpp_f<0x124>(c2);
;     ssq += dpp_f<0x128>(ssq); bon += dpp_f<0x128>(bon); c1 += dpp_f<0x128>(c1); c2 += dpp_f<0x128>(c2);
;     const float inv = __builtin_amdgcn_rsqf(fmaxf(ssq, 1e-24f));
;     f32x4 o_al, o_be, o_wr;
; #pragma unroll
;     for (int j = 0; j < 4; ++j) { o_al[j] = -(kn[j] * inv); o_be[j] = bu[j] * inv; o_wr[j] = dec[j] * rr[j]; }
;     LAS f32x4* s4 = (LAS f32x4*)slot;
;     s4[cq] = (f32x4){dec[0], dec[1], dec[2], dec[3]}; s4[16 + cq] = (f32x4){k2[0], k2[1], k2[2], k2[3]}; s4[32 + cq] = o_al; s4[48 + cq] = o_be; s4[64 + cq] = o_wr;
;     s4[80 + cq] = (f32x4){vv[0], vv[1], vv[2], vv[3]};
;     if (cq == 0) *(LAS f32x2*)(slot + 384) = (f32x2){c1 * inv, c2};
;     return bon;
; }
.LBB0_1109:
	s_waitcnt vmcnt(8)
	v_lshlrev_b32_e32 v108, 16, v46
	v_and_b32_e32 v109, 0xffff0000, v46
	v_lshlrev_b32_e32 v110, 16, v38
	v_and_b32_e32 v111, 0xffff0000, v38
	v_pk_add_f32 v[110:111], v[110:111], v[108:109] neg_lo:[0,1] neg_hi:[0,1]
	v_lshlrev_b32_e32 v140, 16, v39
	v_pk_fma_f32 v[144:145], v[6:7], v[110:111], v[108:109]
	v_lshlrev_b32_e32 v110, 16, v47
	v_and_b32_e32 v111, 0xffff0000, v47
	v_and_b32_e32 v141, 0xffff0000, v39
	v_pk_add_f32 v[140:141], v[140:141], v[110:111] neg_lo:[0,1] neg_hi:[0,1]
	v_lshlrev_b32_e32 v118, 16, v40
	v_and_b32_e32 v119, 0xffff0000, v40
	v_pk_fma_f32 v[146:147], v[8:9], v[140:141], v[110:111]
	v_lshlrev_b32_e32 v140, 16, v34
	v_and_b32_e32 v141, 0xffff0000, v34
	s_waitcnt vmcnt(3)
	v_lshlrev_b32_e32 v142, 16, v48
	v_and_b32_e32 v143, 0xffff0000, v48
	v_pk_add_f32 v[140:141], v[140:141], v[118:119] neg_lo:[0,1] neg_hi:[0,1]
	v_pk_add_f32 v[148:149], v[142:143], -1.0 op_sel_hi:[1,0]
	v_pk_fma_f32 v[140:141], v[2:3], v[140:141], v[118:119]
	v_pk_fma_f32 v[148:149], v[18:19], v[148:149], 1.0 op_sel_hi:[1,1,0]
	v_pk_mul_f32 v[154:155], v[14:15], v[140:141]
	v_pk_mul_f32 v[148:149], v[148:149], v[140:141]
	v_cvt_f32_f16_sdwa v141, v44 dst_sel:DWORD dst_unused:UNUSED_PAD src0_sel:WORD_1
	v_cvt_f32_f16_e32 v140, v44
	v_lshlrev_b32_e32 v114, 16, v36
	v_and_b32_e32 v115, 0xffff0000, v36
	v_lshlrev_b32_e32 v156, 16, v42
	v_and_b32_e32 v157, 0xffff0000, v42
	v_pk_add_f32 v[152:153], v[140:141], 1.0 op_sel_hi:[1,0] neg_lo:[1,0] neg_hi:[1,0]
	v_pk_add_f32 v[140:141], v[156:157], v[114:115] neg_lo:[0,1] neg_hi:[0,1]
	v_lshlrev_b32_e32 v116, 16, v41
	v_pk_fma_f32 v[164:165], v[10:11], v[140:141], v[114:115]
	v_and_b32_e32 v117, 0xffff0000, v41
	v_pk_mul_f32 v[140:141], v[164:165], v[148:149]
	v_pk_mul_f32 v[150:151], v[154:155], v[154:155]
	v_fma_f32 v33, v22, v140, 0
	v_add_f32_e32 v28, 0, v140
	v_fmac_f32_e32 v33, v23, v141
	v_add_f32_e32 v168, v141, v28
	v_lshlrev_b32_e32 v140, 16, v35
	v_and_b32_e32 v141, 0xffff0000, v35
	v_pk_add_f32 v[140:141], v[140:141], v[116:117] neg_lo:[0,1] neg_hi:[0,1]
	v_add_f32_e32 v28, v150, v151
	v_pk_fma_f32 v[140:141], v[4:5], v[140:141], v[116:117]
	v_pk_mul_f32 v[142:143], v[154:155], v[142:143]
	v_pk_mul_f32 v[158:159], v[16:17], v[140:141]
	v_pk_mul_f32 v[156:157], v[164:165], v[142:143]
	v_pk_mul_f32 v[160:161], v[158:159], v[158:159]
	v_add_f32_e32 v81, 0, v156
	v_add_f32_e32 v28, v160, v28
	v_add_f32_e32 v28, v161, v28
	v_add_f32_e32 v81, v157, v81
	v_lshlrev_b32_e32 v156, 16, v49
	v_add_f32_dpp v28, v28, v28 row_ror:1 row_mask:0xf bank_mask:0xf bound_ctrl:1
	v_and_b32_e32 v157, 0xffff0000, v49
	v_lshlrev_b32_e32 v112, 16, v37
	v_add_f32_dpp v28, v28, v28 row_ror:2 row_mask:0xf bank_mask:0xf bound_ctrl:1
	v_and_b32_e32 v113, 0xffff0000, v37
	v_pk_add_f32 v[162:163], v[156:157], -1.0 op_sel_hi:[1,0]
	v_add_f32_dpp v28, v28, v28 row_ror:4 row_mask:0xf bank_mask:0xf bound_ctrl:1
	v_pk_fma_f32 v[150:151], v[20:21], v[162:163], 1.0 op_sel_hi:[1,1,0]
	v_pk_mul_f32 v[164:165], v[164:165], 1.0 op_sel_hi:[1,0]
	v_add_f32_dpp v28, v28, v28 row_ror:8 row_mask:0xf bank_mask:0xf bound_ctrl:1
	v_max_f32_e32 v28, 0x179abe15, v28
	v_rsq_f32_e32 v28, v28
	v_pk_mul_f32 v[150:151], v[150:151], v[140:141]
	v_pk_mul_f32 v[140:141], v[158:159], v[156:157]
	v_pk_mul_f32 v[160:161], v[142:143], v[28:29] op_sel_hi:[1,0]
	v_lshlrev_b32_e32 v142, 16, v43
	v_and_b32_e32 v143, 0xffff0000, v43
	v_pk_add_f32 v[142:143], v[142:143], v[112:113] neg_lo:[0,1] neg_hi:[0,1]
	v_pk_mul_f32 v[162:163], v[140:141], v[28:29] op_sel_hi:[1,0]
	v_pk_fma_f32 v[166:167], v[12:13], v[142:143], v[112:113]
	v_pk_mul_f32 v[156:157], v[154:155], v[28:29] op_sel_hi:[1,0] neg_lo:[0,1] neg_hi:[0,1]
	v_pk_mul_f32 v[142:143], v[166:167], v[150:151]
	v_pk_mul_f32 v[140:141], v[166:167], v[140:141]
	v_fmac_f32_e32 v33, v24, v142
	v_add_f32_e32 v142, v142, v168
	v_add_f32_e32 v81, v140, v81
	v_cvt_f32_f16_sdwa v155, v45 dst_sel:DWORD dst_unused:UNUSED_PAD src0_sel:WORD_1
	v_cvt_f32_f16_e32 v154, v45
	v_fmac_f32_e32 v33, v25, v143
	v_add_f32_e32 v140, v143, v142
	v_add_f32_e32 v81, v141, v81
	v_add_f32_dpp v33, v33, v33 row_ror:1 row_mask:0xf bank_mask:0xf bound_ctrl:1
	v_add_f32_dpp v140, v140, v140 row_ror:1 row_mask:0xf bank_mask:0xf bound_ctrl:1
	v_add_f32_dpp v81, v81, v81 row_ror:1 row_mask:0xf bank_mask:0xf bound_ctrl:1
	v_add_f32_dpp v33, v33, v33 row_ror:2 row_mask:0xf bank_mask:0xf bound_ctrl:1
	v_add_f32_dpp v140, v140, v140 row_ror:2 row_mask:0xf bank_mask:0xf bound_ctrl:1
	v_add_f32_dpp v81, v81, v81 row_ror:2 row_mask:0xf bank_mask:0xf bound_ctrl:1
	v_add_f32_dpp v33, v33, v33 row_ror:4 row_mask:0xf bank_mask:0xf bound_ctrl:1
	v_add_f32_dpp v140, v140, v140 row_ror:4 row_mask:0xf bank_mask:0xf bound_ctrl:1
	v_add_f32_dpp v141, v81, v81 row_ror:4 row_mask:0xf bank_mask:0xf bound_ctrl:1
	v_mov_b32_e32 v142, 0
	v_mov_b32_e32 v143, 0
	v_mov_b32_e32 v81, 0
	v_pk_add_f32 v[154:155], v[154:155], 1.0 op_sel_hi:[1,0] neg_lo:[1,0] neg_hi:[1,0]
	v_mov_b32_dpp v142, v141 row_ror:8 row_mask:0xf bank_mask:0xf
	v_mov_b32_dpp v143, v140 row_ror:8 row_mask:0xf bank_mask:0xf
	v_mov_b32_dpp v81, v33 row_ror:8 row_mask:0xf bank_mask:0xf
	v_pk_mul_f32 v[158:159], v[158:159], v[28:29] op_sel_hi:[1,0] neg_lo:[0,1] neg_hi:[0,1]
	v_pk_mul_f32 v[166:167], v[166:167], 1.0 op_sel_hi:[1,0]
	v_mov_b32_e32 v174, v152
	v_mov_b32_e32 v175, v153
	v_mov_b32_e32 v176, v154
	v_mov_b32_e32 v177, v155
	v_mov_b32_e32 v178, v148
	v_mov_b32_e32 v179, v149
	v_mov_b32_e32 v180, v150
	v_mov_b32_e32 v181, v151
	v_mov_b32_e32 v182, v156
	v_mov_b32_e32 v183, v157
	v_mov_b32_e32 v184, v158
	v_mov_b32_e32 v185, v159
	v_mov_b32_e32 v186, v160
	v_mov_b32_e32 v187, v161
	v_mov_b32_e32 v188, v162
	v_mov_b32_e32 v189, v163
	v_mov_b32_e32 v190, v164
	v_mov_b32_e32 v191, v165
	v_mov_b32_e32 v192, v166
	v_mov_b32_e32 v193, v167
	v_mov_b32_e32 v194, v127
	ds_write_b128 v127, v[144:147] offset:51456
	s_nop 7
	s_nop 7
	s_and_saveexec_b64 s[52:53], s[4:5]
	v_add_f32_e32 v141, v141, v142
	v_mul_f32_e32 v142, v141, v28
	v_add_f32_e32 v143, v140, v143
	ds_write_b64 v126, v[142:143] offset:51712
	s_or_b64 exec, exec, s[52:53]
	s_waitcnt vmcnt(17)
; #define LAS __attribute__((address_space(3)))
; __device__ __forceinline__ float scan_prepare(const ScanRegs& R, const u32x2 qr_, const u32x2 qk_, const u32x2 qv_, LAS float* slot, int cq, const f32x4 mur, const f32x4 muk, const f32x4 muv, const f32x4 kkc, const f32x4 kac, const f32x4 rkc) {
;     float pr[4], pk[4], pv[4], qr[4], qk[4], qv[4], av[4], om[4];
;     unpack4(R.pr, pr); unpack4(R.pk, pk); unpack4(R.pv, pv); unpack4(qr_, qr); unpack4(qk_, qk); unpack4(qv_, qv); unpack4(R.as, av);
;     om[0] = f16_to_f((unsigned short)(R.wl.x & 0xffffu)); om[1] = f16_to_f((unsigned short)(R.wl.x >> 16)); om[2] = f16_to_f((unsigned short)(R.wl.y & 0xffffu)); om[3] = f16_to_f((unsigned short)(R.wl.y >> 16));
;     float rr[4], vv[4], kn[4], k2[4], dec[4], bu[4];
;     float ssq = 0.f, bon = 0.f, c1 = 0.f, c2 = 0.f;
; #pragma unroll
;     for (int j = 0; j < 4; ++j) {
;         rr[j] = pr[j] + (qr[j] - pr[j]) * mur[j]; const float kk0 = pk[j] + (qk[j] - pk[j]) * muk[j]; vv[j] = pv[j] + (qv[j] - pv[j]) * muv[j];
;         dec[j] = 1.0f - om[j];
;         kn[j] = kk0 * kkc[j]; ssq += kn[j] * kn[j];
;         k2[j] = kk0 * (1.0f + (av[j] - 1.0f) * kac[j]);
;         const float t = rr[j] * k2[j]; bon += t * rkc[j]; c2 += t;
;         bu[j] = kn[j] * av[j]; c1 += bu[j] * rr[j];
;     }
;     ssq += dpp_f<0x121>(ssq); bon += dpp_f<0x121>(bon); c1 += dpp_f<0x121>(c1); c2 += dpp_f<0x121>(c2);
;     ssq += dpp_f<0x122>(ssq); bon += dpp_f<0x122>(bon); c1 += dpp_f<0x122>(c1); c2 += dpp_f<0x122>(c2);
;     ssq += dpp_f<0x124>(ssq); bon += dpp_f<0x124>(bon); c1 += dpp_f<0x124>(c1); c2 += dpp_f<0x124>(c2);
;     ssq += dpp_f<0x128>(ssq); bon += dpp_f<0x128>(bon); c1 += dpp_f<0x128>(c1); c2 += dpp_f<0x128>(c2);
;     const float inv = __builtin_amdgcn_rsqf(fmaxf(ssq, 1e-24f));
;     f32x4 o_al, o_be, o_wr;
; #pragma unroll
;     for (int j = 0; j < 4; ++j) { o_al[j] = -(kn[j] * inv); o_be[j] = bu[j] * inv; o_wr[j] = dec[j] * rr[j]; }
;     LAS f32x4* s4 = (LAS f32x4*)slot;
;     s4[cq] = (f32x4){dec[0], dec[1], dec[2], dec[3]}; s4[16 + cq] = (f32x4){k2[0], k2[1], k2[2], k2[3]}; s4[32 + cq] = o_al; s4[48 + cq] = o_be; s4[64 + cq] = o_wr;
;     s4[80 + cq] = (f32x4){vv[0], vv[1], vv[2], vv[3]};
;     if (cq == 0) *(LAS f32x2*)(slot + 384) = (f32x2){c1 * inv, c2};
;     return bon;
; }
	v_lshlrev_b32_e32 v140, 16, v50
	v_and_b32_e32 v141, 0xffff0000, v50
	s_waitcnt vmcnt(2)
	v_lshlrev_b32_e32 v142, 16, v58
	v_and_b32_e32 v143, 0xffff0000, v58
	v_pk_add_f32 v[118:119], v[118:119], v[140:141] neg_lo:[0,1] neg_hi:[0,1]
	v_lshlrev_b32_e32 v150, 16, v59
	v_pk_fma_f32 v[118:119], v[2:3], v[118:119], v[140:141]
	v_pk_add_f32 v[140:141], v[142:143], -1.0 op_sel_hi:[1,0]
	v_pk_mul_f32 v[146:147], v[14:15], v[118:119]
	v_pk_fma_f32 v[140:141], v[18:19], v[140:141], 1.0 op_sel_hi:[1,1,0]
	v_pk_mul_f32 v[152:153], v[146:147], v[142:143]
	v_pk_mul_f32 v[140:141], v[140:141], v[118:119]
	v_cvt_f32_f16_sdwa v119, v52 dst_sel:DWORD dst_unused:UNUSED_PAD src0_sel:WORD_1
	v_cvt_f32_f16_e32 v118, v52
	s_waitcnt vmcnt(6)
	v_lshlrev_b32_e32 v142, 16, v82
	v_and_b32_e32 v143, 0xffff0000, v82
	v_pk_add_f32 v[114:115], v[114:115], v[142:143] neg_lo:[0,1] neg_hi:[0,1]
	v_pk_add_f32 v[144:145], v[118:119], 1.0 op_sel_hi:[1,0] neg_lo:[1,0] neg_hi:[1,0]
	v_pk_fma_f32 v[118:119], v[10:11], v[114:115], v[142:143]
	v_pk_mul_f32 v[148:149], v[146:147], v[146:147]
	v_pk_mul_f32 v[114:115], v[118:119], v[140:141]
	v_pk_mul_f32 v[142:143], v[118:119], v[152:153]
	v_fma_f32 v156, v22, v114, 0
	v_add_f32_e32 v28, 0, v114
	v_add_f32_e32 v114, 0, v142
	v_fmac_f32_e32 v156, v23, v115
	v_add_f32_e32 v157, v115, v28
	v_add_f32_e32 v164, v143, v114
	v_lshlrev_b32_e32 v114, 16, v51
	v_and_b32_e32 v115, 0xffff0000, v51
	v_pk_add_f32 v[116:117], v[116:117], v[114:115] neg_lo:[0,1] neg_hi:[0,1]
	v_add_f32_e32 v28, v148, v149
	v_pk_fma_f32 v[114:115], v[4:5], v[116:117], v[114:115]
	v_and_b32_e32 v151, 0xffff0000, v59
	v_pk_mul_f32 v[116:117], v[16:17], v[114:115]
	v_pk_add_f32 v[154:155], v[150:151], -1.0 op_sel_hi:[1,0]
	v_pk_mul_f32 v[142:143], v[116:117], v[116:117]
	s_waitcnt vmcnt(5)
	v_lshlrev_b32_e32 v160, 16, v88
	v_add_f32_e32 v28, v142, v28
	v_add_f32_e32 v28, v143, v28
	v_pk_fma_f32 v[142:143], v[20:21], v[154:155], 1.0 op_sel_hi:[1,1,0]
	v_and_b32_e32 v161, 0xffff0000, v88
	v_add_f32_dpp v28, v28, v28 row_ror:1 row_mask:0xf bank_mask:0xf bound_ctrl:1
	v_pk_mul_f32 v[142:143], v[142:143], v[114:115]
	v_pk_mul_f32 v[114:115], v[116:117], v[150:151]
	v_add_f32_dpp v28, v28, v28 row_ror:2 row_mask:0xf bank_mask:0xf bound_ctrl:1
	v_lshlrev_b32_e32 v162, 16, v89
	v_and_b32_e32 v163, 0xffff0000, v89
	v_add_f32_dpp v28, v28, v28 row_ror:4 row_mask:0xf bank_mask:0xf bound_ctrl:1
	v_pk_add_f32 v[108:109], v[108:109], v[160:161] neg_lo:[0,1] neg_hi:[0,1]
	v_pk_add_f32 v[110:111], v[110:111], v[162:163] neg_lo:[0,1] neg_hi:[0,1]
	v_add_f32_dpp v28, v28, v28 row_ror:8 row_mask:0xf bank_mask:0xf bound_ctrl:1
	v_max_f32_e32 v28, 0x179abe15, v28
	v_rsq_f32_e32 v28, v28
	v_pk_fma_f32 v[110:111], v[8:9], v[110:111], v[162:163]
	v_pk_fma_f32 v[108:109], v[6:7], v[108:109], v[160:161]
	v_pk_mul_f32 v[150:151], v[116:117], v[28:29] op_sel_hi:[1,0] neg_lo:[0,1] neg_hi:[0,1]
	v_lshlrev_b32_e32 v116, 16, v83
	v_and_b32_e32 v117, 0xffff0000, v83
	v_pk_add_f32 v[112:113], v[112:113], v[116:117] neg_lo:[0,1] neg_hi:[0,1]
	v_pk_mul_f32 v[154:155], v[114:115], v[28:29] op_sel_hi:[1,0]
	v_pk_fma_f32 v[158:159], v[12:13], v[112:113], v[116:117]
	v_pk_mul_f32 v[148:149], v[146:147], v[28:29] op_sel_hi:[1,0] neg_lo:[0,1] neg_hi:[0,1]
	v_pk_mul_f32 v[112:113], v[158:159], v[142:143]
	v_pk_mul_f32 v[114:115], v[158:159], v[114:115]
	v_fmac_f32_e32 v156, v24, v112
	v_add_f32_e32 v112, v112, v157
	v_add_f32_e32 v114, v114, v164
	v_cvt_f32_f16_sdwa v147, v53 dst_sel:DWORD dst_unused:UNUSED_PAD src0_sel:WORD_1
	v_cvt_f32_f16_e32 v146, v53
	v_fmac_f32_e32 v156, v25, v113
	v_add_f32_e32 v112, v113, v112
	v_add_f32_e32 v113, v115, v114
	v_add_f32_dpp v114, v156, v156 row_ror:1 row_mask:0xf bank_mask:0xf bound_ctrl:1
	v_add_f32_dpp v112, v112, v112 row_ror:1 row_mask:0xf bank_mask:0xf bound_ctrl:1
	v_add_f32_dpp v113, v113, v113 row_ror:1 row_mask:0xf bank_mask:0xf bound_ctrl:1
	v_add_f32_dpp v114, v114, v114 row_ror:2 row_mask:0xf bank_mask:0xf bound_ctrl:1
	v_add_f32_dpp v116, v112, v112 row_ror:2 row_mask:0xf bank_mask:0xf bound_ctrl:1
	v_add_f32_dpp v113, v113, v113 row_ror:2 row_mask:0xf bank_mask:0xf bound_ctrl:1
	v_add_f32_dpp v112, v114, v114 row_ror:4 row_mask:0xf bank_mask:0xf bound_ctrl:1
	v_add_f32_dpp v114, v116, v116 row_ror:4 row_mask:0xf bank_mask:0xf bound_ctrl:1
	v_add_f32_dpp v115, v113, v113 row_ror:4 row_mask:0xf bank_mask:0xf bound_ctrl:1
	v_mov_b32_e32 v116, 0
	v_mov_b32_e32 v117, 0
	v_mov_b32_e32 v113, 0
	v_pk_add_f32 v[146:147], v[146:147], 1.0 op_sel_hi:[1,0] neg_lo:[1,0] neg_hi:[1,0]
	v_mov_b32_dpp v116, v115 row_ror:8 row_mask:0xf bank_mask:0xf
	v_mov_b32_dpp v117, v114 row_ror:8 row_mask:0xf bank_mask:0xf
	v_mov_b32_dpp v113, v112 row_ror:8 row_mask:0xf bank_mask:0xf
	v_pk_mul_f32 v[152:153], v[152:153], v[28:29] op_sel_hi:[1,0]
	v_pk_mul_f32 v[156:157], v[118:119], 1.0 op_sel_hi:[1,0]
	v_pk_mul_f32 v[158:159], v[158:159], 1.0 op_sel_hi:[1,0]
	ds_write_b128 v129, v[108:111] offset:51456
	v_pk_mul_f32 v[196:197], v[174:175], v[144:145]
	v_pk_mul_f32 v[198:199], v[176:177], v[146:147]
	ds_bpermute_b32 v200, v233, v196
	ds_bpermute_b32 v201, v233, v197
	ds_bpermute_b32 v202, v233, v198
	ds_bpermute_b32 v203, v233, v199
	s_waitcnt lgkmcnt(0)
; #define LAS __attribute__((address_space(3)))
; __device__ __forceinline__ float scan_prepare(const ScanRegs& R, const u32x2 qr_, const u32x2 qk_, const u32x2 qv_, LAS float* slot, int cq, const f32x4 mur, const f32x4 muk, const f32x4 muv, const f32x4 kkc, const f32x4 kac, const f32x4 rkc) {
;     ...
;     f32x4 o_al, o_be, o_wr;
; #pragma unroll
;     for (int j = 0; j < 4; ++j) { o_al[j] = -(kn[j] * inv); o_be[j] = bu[j] * inv; o_wr[j] = dec[j] * rr[j]; }
;     LAS f32x4* s4 = (LAS f32x4*)slot;
;     s4[cq] = (f32x4){dec[0], dec[1], dec[2], dec[3]}; s4[16 + cq] = (f32x4){k2[0], k2[1], k2[2], k2[3]}; s4[32 + cq] = o_al; s4[48 + cq] = o_be; s4[64 + cq] = o_wr;
;     s4[80 + cq] = (f32x4){vv[0], vv[1], vv[2], vv[3]};
;     if (cq == 0) *(LAS f32x2*)(slot + 384) = (f32x2){c1 * inv, c2};
	v_fma_f32 v200, v200, v235, v236
	v_fma_f32 v201, v201, v235, v236
	v_fma_f32 v202, v202, v235, v236
	v_fma_f32 v203, v203, v235, v236
	v_pk_mul_f32 v[204:205], v[196:197], v[200:201]
	v_pk_mul_f32 v[206:207], v[198:199], v[202:203]
	ds_bpermute_b32 v208, v234, v204
	ds_bpermute_b32 v209, v234, v205
	ds_bpermute_b32 v210, v234, v206
	ds_bpermute_b32 v211, v234, v207
	s_waitcnt lgkmcnt(0)
	v_fma_f32 v208, v208, v237, v238
	v_fma_f32 v209, v209, v237, v238
	v_fma_f32 v210, v210, v237, v238
	v_fma_f32 v211, v211, v237, v238
	v_pk_mul_f32 v[212:213], v[200:201], v[208:209]
	v_pk_mul_f32 v[214:215], v[202:203], v[210:211]
	v_pk_mul_f32 v[216:217], v[212:213], v[174:175]
	v_pk_mul_f32 v[218:219], v[214:215], v[176:177]
	v_pk_mul_f32 v[220:221], v[216:217], v[144:145]
	v_pk_mul_f32 v[222:223], v[218:219], v[146:147]
	v_rcp_f32_e32 v224, v216
	v_rcp_f32_e32 v225, v217
	v_rcp_f32_e32 v226, v218
	v_rcp_f32_e32 v227, v219
	v_rcp_f32_e32 v228, v220
	v_rcp_f32_e32 v229, v221
	v_rcp_f32_e32 v230, v222
	v_rcp_f32_e32 v231, v223
	s_nop 0
	v_pk_mul_f32 v[182:183], v[182:183], v[212:213]
	v_pk_mul_f32 v[184:185], v[184:185], v[214:215]
	v_pk_mul_f32 v[178:179], v[178:179], v[224:225]
	v_pk_mul_f32 v[180:181], v[180:181], v[226:227]
	ds_write_b128 v194, v[178:181] offset:50432
	s_nop 7
	s_nop 7
	v_pk_mul_f32 v[186:187], v[186:187], v[224:225]
	v_pk_mul_f32 v[188:189], v[188:189], v[226:227]
	ds_write_b128 v194, v[182:185] offset:50688
	s_nop 7
	s_nop 7
	v_pk_mul_f32 v[190:191], v[190:191], v[216:217]
	v_pk_mul_f32 v[192:193], v[192:193], v[218:219]
	ds_write_b128 v194, v[186:189] offset:50944
	s_nop 7
	s_nop 7
	v_pk_mul_f32 v[240:241], v[140:141], v[228:229]
	v_pk_mul_f32 v[242:243], v[142:143], v[230:231]
	ds_write_b128 v194, v[190:193] offset:51200
	s_nop 7
	s_nop 7
	v_pk_mul_f32 v[244:245], v[148:149], v[216:217]
	v_pk_mul_f32 v[246:247], v[150:151], v[218:219]
	ds_write_b128 v129, v[220:223] offset:50176
	s_nop 7
	s_nop 7
	v_pk_mul_f32 v[196:197], v[152:153], v[228:229]
	v_pk_mul_f32 v[198:199], v[154:155], v[230:231]
	ds_write_b128 v129, v[240:243] offset:50432
	s_nop 7
	s_nop 7
	v_pk_mul_f32 v[200:201], v[156:157], v[220:221]
	v_pk_mul_f32 v[202:203], v[158:159], v[222:223]
	ds_write_b128 v129, v[244:247] offset:50688
	s_nop 7
	s_nop 7
	ds_write_b128 v129, v[196:199] offset:50944
	s_nop 7
	s_nop 7
	ds_write_b128 v129, v[200:203] offset:51200
	s_nop 7
	s_nop 7
	s_and_saveexec_b64 s[52:53], s[4:5]
	s_cbranch_execz .LBB0_1121
	v_add_f32_e32 v108, v115, v116
	v_mul_f32_e32 v108, v108, v28
	v_add_f32_e32 v109, v114, v117
	ds_write_b64 v128, v[108:109] offset:51712
	s_or_b64 exec, exec, s[52:53]
	s_and_saveexec_b64 s[52:53], s[44:45]
	s_cbranch_execnz .LBB0_1122

; #define LAS __attribute__((address_space(3)))
; __device__ __forceinline__ float scan_prepare(const ScanRegs& R, const u32x2 qr_, const u32x2 qk_, const u32x2 qv_, LAS float* slot, int cq, const f32x4 mur, const f32x4 muk, const f32x4 muv, const f32x4 kkc, const f32x4 kac, const f32x4 rkc) {
;     float pr[4], pk[4], pv[4], qr[4], qk[4], qv[4], av[4], om[4];
;     unpack4(R.pr, pr); unpack4(R.pk, pk); unpack4(R.pv, pv); unpack4(qr_, qr); unpack4(qk_, qk); unpack4(qv_, qv); unpack4(R.as, av);
;     om[0] = f16_to_f((unsigned short)(R.wl.x & 0xffffu)); om[1] = f16_to_f((unsigned short)(R.wl.x >> 16)); om[2] = f16_to_f((unsigned short)(R.wl.y & 0xffffu)); om[3] = f16_to_f((unsigned short)(R.wl.y >> 16));
;     float rr[4], vv[4], kn[4], k2[4], dec[4], bu[4];
;     float ssq = 0.f, bon = 0.f, c1 = 0.f, c2 = 0.f;
; #pragma unroll
;     for (int j = 0; j < 4; ++j) {
;         rr[j] = pr[j] + (qr[j] - pr[j]) * mur[j]; const float kk0 = pk[j] + (qk[j] - pk[j]) * muk[j]; vv[j] = pv[j] + (qv[j] - pv[j]) * muv[j];
;         dec[j] = 1.0f - om[j];
;         kn[j] = kk0 * kkc[j]; ssq += kn[j] * kn[j];
;         k2[j] = kk0 * (1.0f + (av[j] - 1.0f) * kac[j]);
;         const float t = rr[j] * k2[j]; bon += t * rkc[j]; c2 += t;
;         bu[j] = kn[j] * av[j]; c1 += bu[j] * rr[j];
;     }
;     ssq += dpp_f<0x121>(ssq); bon += dpp_f<0x121>(bon); c1 += dpp_f<0x121>(c1); c2 += dpp_f<0x121>(c2);
;     ssq += dpp_f<0x122>(ssq); bon += dpp_f<0x122>(bon); c1 += dpp_f<0x122>(c1); c2 += dpp_f<0x122>(c2);
;     ssq += dpp_f<0x124>(ssq); bon += dpp_f<0x124>(bon); c1 += dpp_f<0x124>(c1); c2 += dpp_f<0x124>(c2);
;     ssq += dpp_f<0x128>(ssq); bon += dpp_f<0x128>(bon); c1 += dpp_f<0x128>(c1); c2 += dpp_f<0x128>(c2);
;     const float inv = __builtin_amdgcn_rsqf(fmaxf(ssq, 1e-24f));
;     f32x4 o_al, o_be, o_wr;
; #pragma unroll
;     for (int j = 0; j < 4; ++j) { o_al[j] = -(kn[j] * inv); o_be[j] = bu[j] * inv; o_wr[j] = dec[j] * rr[j]; }
;     LAS f32x4* s4 = (LAS f32x4*)slot;
;     s4[cq] = (f32x4){dec[0], dec[1], dec[2], dec[3]}; s4[16 + cq] = (f32x4){k2[0], k2[1], k2[2], k2[3]}; s4[32 + cq] = o_al; s4[48 + cq] = o_be; s4[64 + cq] = o_wr;
;     s4[80 + cq] = (f32x4){vv[0], vv[1], vv[2], vv[3]};
;     if (cq == 0) *(LAS f32x2*)(slot + 384) = (f32x2){c1 * inv, c2};
;     return bon;
; }
.LBB0_1115:
	v_add_u32_e32 v28, v120, v130
	s_waitcnt lgkmcnt(0)
	s_barrier
	ds_read_b128 v[108:111], v28
	v_lshl_add_u64 v[112:113], s[92:93], 0, v[100:101]
	v_add_co_u32_e32 v112, vcc, s68, v112
	s_cmpk_gt_u32 s14, 0xfd
	s_waitcnt lgkmcnt(0)
	v_add_f32_e32 v28, v108, v109
	v_add_f32_e32 v33, v110, v111
	v_add_f32_e32 v28, v28, v33
	v_bfe_u32 v33, v28, 16, 1
	v_add3_u32 v28, v28, v33, s67
	v_addc_co_u32_e32 v113, vcc, 0, v113, vcc
	global_store_short_d16_hi v[112:113], v28, off
	v_add_u32_e32 v28, v120, v131
	ds_read_b128 v[108:111], v28
	s_cselect_b64 s[52:53], -1, 0
	s_and_b64 vcc, exec, s[52:53]
	s_waitcnt lgkmcnt(0)
	v_add_f32_e32 v28, v108, v109
	v_add_f32_e32 v33, v110, v111
	v_add_f32_e32 v28, v28, v33
	v_bfe_u32 v33, v28, 16, 1
	v_add3_u32 v28, v28, v33, s67
	global_store_short_d16_hi v[112:113], v28, off offset:2048
	s_cbranch_vccnz .LBB0_1106
	v_lshlrev_b32_e32 v108, 16, v76
	v_and_b32_e32 v109, 0xffff0000, v76
	v_lshlrev_b32_e32 v110, 16, v62
	v_and_b32_e32 v111, 0xffff0000, v62
	v_pk_add_f32 v[110:111], v[110:111], v[108:109] neg_lo:[0,1] neg_hi:[0,1]
	v_lshlrev_b32_e32 v140, 16, v63
	v_pk_fma_f32 v[144:145], v[6:7], v[110:111], v[108:109]
	v_lshlrev_b32_e32 v110, 16, v77
	v_and_b32_e32 v111, 0xffff0000, v77
	v_and_b32_e32 v141, 0xffff0000, v63
	v_pk_add_f32 v[140:141], v[140:141], v[110:111] neg_lo:[0,1] neg_hi:[0,1]
	v_lshlrev_b32_e32 v118, 16, v64
	v_and_b32_e32 v119, 0xffff0000, v64
	v_pk_fma_f32 v[146:147], v[8:9], v[140:141], v[110:111]
	v_lshlrev_b32_e32 v140, 16, v54
	v_and_b32_e32 v141, 0xffff0000, v54
	s_waitcnt vmcnt(3)
	v_lshlrev_b32_e32 v142, 16, v86
	v_and_b32_e32 v143, 0xffff0000, v86
	v_pk_add_f32 v[140:141], v[140:141], v[118:119] neg_lo:[0,1] neg_hi:[0,1]
	v_pk_add_f32 v[148:149], v[142:143], -1.0 op_sel_hi:[1,0]
	v_pk_fma_f32 v[140:141], v[2:3], v[140:141], v[118:119]
	v_pk_fma_f32 v[148:149], v[18:19], v[148:149], 1.0 op_sel_hi:[1,1,0]
	v_pk_mul_f32 v[154:155], v[14:15], v[140:141]
	v_pk_mul_f32 v[148:149], v[140:141], v[148:149]
	v_cvt_f32_f16_sdwa v141, v72 dst_sel:DWORD dst_unused:UNUSED_PAD src0_sel:WORD_1
	v_cvt_f32_f16_e32 v140, v72
	v_lshlrev_b32_e32 v114, 16, v56
	v_and_b32_e32 v115, 0xffff0000, v56
	v_lshlrev_b32_e32 v156, 16, v68
	v_and_b32_e32 v157, 0xffff0000, v68
	v_pk_add_f32 v[152:153], v[140:141], 1.0 op_sel_hi:[1,0] neg_lo:[1,0] neg_hi:[1,0]
	v_pk_add_f32 v[140:141], v[156:157], v[114:115] neg_lo:[0,1] neg_hi:[0,1]
	v_lshlrev_b32_e32 v116, 16, v65
	v_pk_fma_f32 v[164:165], v[10:11], v[140:141], v[114:115]
	v_and_b32_e32 v117, 0xffff0000, v65
	v_pk_mul_f32 v[140:141], v[164:165], v[148:149]
	v_pk_mul_f32 v[150:151], v[154:155], v[154:155]
	v_fma_f32 v33, v22, v140, 0
	v_add_f32_e32 v28, 0, v140
	v_fmac_f32_e32 v33, v23, v141
	v_add_f32_e32 v168, v141, v28
	v_lshlrev_b32_e32 v140, 16, v55
	v_and_b32_e32 v141, 0xffff0000, v55
	v_pk_add_f32 v[140:141], v[140:141], v[116:117] neg_lo:[0,1] neg_hi:[0,1]
	v_add_f32_e32 v28, v150, v151
	v_pk_fma_f32 v[140:141], v[4:5], v[140:141], v[116:117]
	v_pk_mul_f32 v[142:143], v[154:155], v[142:143]
	v_pk_mul_f32 v[158:159], v[16:17], v[140:141]
	v_pk_mul_f32 v[156:157], v[164:165], v[142:143]
	v_pk_mul_f32 v[160:161], v[158:159], v[158:159]
	v_add_f32_e32 v81, 0, v156
	v_add_f32_e32 v28, v160, v28
	v_add_f32_e32 v28, v161, v28
	v_add_f32_e32 v81, v157, v81
	v_lshlrev_b32_e32 v156, 16, v87
	v_add_f32_dpp v28, v28, v28 row_ror:1 row_mask:0xf bank_mask:0xf bound_ctrl:1
	v_and_b32_e32 v157, 0xffff0000, v87
	v_lshlrev_b32_e32 v112, 16, v57
	v_add_f32_dpp v28, v28, v28 row_ror:2 row_mask:0xf bank_mask:0xf bound_ctrl:1
	v_and_b32_e32 v113, 0xffff0000, v57
	v_pk_add_f32 v[162:163], v[156:157], -1.0 op_sel_hi:[1,0]
	v_add_f32_dpp v28, v28, v28 row_ror:4 row_mask:0xf bank_mask:0xf bound_ctrl:1
	v_pk_fma_f32 v[150:151], v[20:21], v[162:163], 1.0 op_sel_hi:[1,1,0]
	v_pk_mul_f32 v[164:165], v[164:165], 1.0 op_sel_hi:[1,0]
	v_add_f32_dpp v28, v28, v28 row_ror:8 row_mask:0xf bank_mask:0xf bound_ctrl:1
	v_max_f32_e32 v28, 0x179abe15, v28
	v_rsq_f32_e32 v28, v28
	v_pk_mul_f32 v[150:151], v[140:141], v[150:151]
	v_pk_mul_f32 v[140:141], v[158:159], v[156:157]
	v_pk_mul_f32 v[160:161], v[142:143], v[28:29] op_sel_hi:[1,0]
	v_lshlrev_b32_e32 v142, 16, v69
	v_and_b32_e32 v143, 0xffff0000, v69
	v_pk_add_f32 v[142:143], v[142:143], v[112:113] neg_lo:[0,1] neg_hi:[0,1]
	v_pk_mul_f32 v[162:163], v[140:141], v[28:29] op_sel_hi:[1,0]
	v_pk_fma_f32 v[166:167], v[12:13], v[142:143], v[112:113]
	v_pk_mul_f32 v[156:157], v[154:155], v[28:29] op_sel_hi:[1,0] neg_lo:[0,1] neg_hi:[0,1]
	v_pk_mul_f32 v[142:143], v[166:167], v[150:151]
	v_pk_mul_f32 v[140:141], v[166:167], v[140:141]
	v_fmac_f32_e32 v33, v24, v142
	v_add_f32_e32 v142, v142, v168
	v_add_f32_e32 v81, v140, v81
	v_cvt_f32_f16_sdwa v155, v73 dst_sel:DWORD dst_unused:UNUSED_PAD src0_sel:WORD_1
	v_cvt_f32_f16_e32 v154, v73
	v_fmac_f32_e32 v33, v25, v143
	v_add_f32_e32 v140, v143, v142
	v_add_f32_e32 v81, v141, v81
	v_add_f32_dpp v33, v33, v33 row_ror:1 row_mask:0xf bank_mask:0xf bound_ctrl:1
	v_add_f32_dpp v140, v140, v140 row_ror:1 row_mask:0xf bank_mask:0xf bound_ctrl:1
	v_add_f32_dpp v81, v81, v81 row_ror:1 row_mask:0xf bank_mask:0xf bound_ctrl:1
	v_add_f32_dpp v33, v33, v33 row_ror:2 row_mask:0xf bank_mask:0xf bound_ctrl:1
	v_add_f32_dpp v140, v140, v140 row_ror:2 row_mask:0xf bank_mask:0xf bound_ctrl:1
	v_add_f32_dpp v81, v81, v81 row_ror:2 row_mask:0xf bank_mask:0xf bound_ctrl:1
	v_add_f32_dpp v33, v33, v33 row_ror:4 row_mask:0xf bank_mask:0xf bound_ctrl:1
	v_add_f32_dpp v140, v140, v140 row_ror:4 row_mask:0xf bank_mask:0xf bound_ctrl:1
	v_add_f32_dpp v141, v81, v81 row_ror:4 row_mask:0xf bank_mask:0xf bound_ctrl:1
	v_mov_b32_e32 v142, 0
	v_mov_b32_e32 v143, 0
	v_mov_b32_e32 v81, 0
	v_pk_add_f32 v[154:155], v[154:155], 1.0 op_sel_hi:[1,0] neg_lo:[1,0] neg_hi:[1,0]
	v_mov_b32_dpp v142, v141 row_ror:8 row_mask:0xf bank_mask:0xf
	v_mov_b32_dpp v143, v140 row_ror:8 row_mask:0xf bank_mask:0xf
	v_mov_b32_dpp v81, v33 row_ror:8 row_mask:0xf bank_mask:0xf
	v_pk_mul_f32 v[158:159], v[158:159], v[28:29] op_sel_hi:[1,0] neg_lo:[0,1] neg_hi:[0,1]
	v_pk_mul_f32 v[166:167], v[166:167], 1.0 op_sel_hi:[1,0]
	v_mov_b32_e32 v174, v152
	v_mov_b32_e32 v175, v153
	v_mov_b32_e32 v176, v154
	v_mov_b32_e32 v177, v155
	v_mov_b32_e32 v178, v148
	v_mov_b32_e32 v179, v149
	v_mov_b32_e32 v180, v150
	v_mov_b32_e32 v181, v151
	v_mov_b32_e32 v182, v156
	v_mov_b32_e32 v183, v157
	v_mov_b32_e32 v184, v158
	v_mov_b32_e32 v185, v159
	v_mov_b32_e32 v186, v160
	v_mov_b32_e32 v187, v161
	v_mov_b32_e32 v188, v162
	v_mov_b32_e32 v189, v163
	v_mov_b32_e32 v190, v164
	v_mov_b32_e32 v191, v165
	v_mov_b32_e32 v192, v166
	v_mov_b32_e32 v193, v167
	v_mov_b32_e32 v194, v127
	ds_write_b128 v127, v[144:147] offset:1280
	s_nop 7
	s_nop 7
	s_and_saveexec_b64 s[56:57], s[4:5]
	v_add_f32_e32 v141, v141, v142
	v_mul_f32_e32 v142, v141, v28
	v_add_f32_e32 v143, v140, v143
	ds_write_b64 v126, v[142:143] offset:1536
	s_or_b64 exec, exec, s[56:57]
	s_waitcnt vmcnt(4)
; #define LAS __attribute__((address_space(3)))
; __device__ __forceinline__ float scan_prepare(const ScanRegs& R, const u32x2 qr_, const u32x2 qk_, const u32x2 qv_, LAS float* slot, int cq, const f32x4 mur, const f32x4 muk, const f32x4 muv, const f32x4 kkc, const f32x4 kac, const f32x4 rkc) {
;     float pr[4], pk[4], pv[4], qr[4], qk[4], qv[4], av[4], om[4];
;     unpack4(R.pr, pr); unpack4(R.pk, pk); unpack4(R.pv, pv); unpack4(qr_, qr); unpack4(qk_, qk); unpack4(qv_, qv); unpack4(R.as, av);
;     om[0] = f16_to_f((unsigned short)(R.wl.x & 0xffffu)); om[1] = f16_to_f((unsigned short)(R.wl.x >> 16)); om[2] = f16_to_f((unsigned short)(R.wl.y & 0xffffu)); om[3] = f16_to_f((unsigned short)(R.wl.y >> 16));
;     float rr[4], vv[4], kn[4], k2[4], dec[4], bu[4];
;     float ssq = 0.f, bon = 0.f, c1 = 0.f, c2 = 0.f;
; #pragma unroll
;     for (int j = 0; j < 4; ++j) {
;         rr[j] = pr[j] + (qr[j] - pr[j]) * mur[j]; const float kk0 = pk[j] + (qk[j] - pk[j]) * muk[j]; vv[j] = pv[j] + (qv[j] - pv[j]) * muv[j];
;         dec[j] = 1.0f - om[j];
;         kn[j] = kk0 * kkc[j]; ssq += kn[j] * kn[j];
;         k2[j] = kk0 * (1.0f + (av[j] - 1.0f) * kac[j]);
;         const float t = rr[j] * k2[j]; bon += t * rkc[j]; c2 += t;
;         bu[j] = kn[j] * av[j]; c1 += bu[j] * rr[j];
;     }
;     ssq += dpp_f<0x121>(ssq); bon += dpp_f<0x121>(bon); c1 += dpp_f<0x121>(c1); c2 += dpp_f<0x121>(c2);
;     ssq += dpp_f<0x122>(ssq); bon += dpp_f<0x122>(bon); c1 += dpp_f<0x122>(c1); c2 += dpp_f<0x122>(c2);
;     ssq += dpp_f<0x124>(ssq); bon += dpp_f<0x124>(bon); c1 += dpp_f<0x124>(c1); c2 += dpp_f<0x124>(c2);
;     ssq += dpp_f<0x128>(ssq); bon += dpp_f<0x128>(bon); c1 += dpp_f<0x128>(c1); c2 += dpp_f<0x128>(c2);
;     const float inv = __builtin_amdgcn_rsqf(fmaxf(ssq, 1e-24f));
;     f32x4 o_al, o_be, o_wr;
; #pragma unroll
;     for (int j = 0; j < 4; ++j) { o_al[j] = -(kn[j] * inv); o_be[j] = bu[j] * inv; o_wr[j] = dec[j] * rr[j]; }
;     LAS f32x4* s4 = (LAS f32x4*)slot;
;     s4[cq] = (f32x4){dec[0], dec[1], dec[2], dec[3]}; s4[16 + cq] = (f32x4){k2[0], k2[1], k2[2], k2[3]}; s4[32 + cq] = o_al; s4[48 + cq] = o_be; s4[64 + cq] = o_wr;
;     s4[80 + cq] = (f32x4){vv[0], vv[1], vv[2], vv[3]};
;     if (cq == 0) *(LAS f32x2*)(slot + 384) = (f32x2){c1 * inv, c2};
;     return bon;
; }
	v_lshlrev_b32_e32 v140, 16, v96
	v_and_b32_e32 v141, 0xffff0000, v96
	s_waitcnt vmcnt(2)
	v_lshlrev_b32_e32 v142, 16, v102
	v_and_b32_e32 v143, 0xffff0000, v102
	v_pk_add_f32 v[118:119], v[118:119], v[140:141] neg_lo:[0,1] neg_hi:[0,1]
	v_lshlrev_b32_e32 v150, 16, v103
	v_pk_fma_f32 v[118:119], v[2:3], v[118:119], v[140:141]
	v_pk_add_f32 v[140:141], v[142:143], -1.0 op_sel_hi:[1,0]
	v_pk_mul_f32 v[146:147], v[14:15], v[118:119]
	v_pk_fma_f32 v[140:141], v[18:19], v[140:141], 1.0 op_sel_hi:[1,1,0]
	v_pk_mul_f32 v[152:153], v[146:147], v[142:143]
	v_pk_mul_f32 v[140:141], v[140:141], v[118:119]
	v_cvt_f32_f16_sdwa v119, v98 dst_sel:DWORD dst_unused:UNUSED_PAD src0_sel:WORD_1
	v_cvt_f32_f16_e32 v118, v98
	v_lshlrev_b32_e32 v142, 16, v84
	v_and_b32_e32 v143, 0xffff0000, v84
	v_pk_add_f32 v[114:115], v[114:115], v[142:143] neg_lo:[0,1] neg_hi:[0,1]
	v_pk_add_f32 v[144:145], v[118:119], 1.0 op_sel_hi:[1,0] neg_lo:[1,0] neg_hi:[1,0]
	v_pk_fma_f32 v[118:119], v[10:11], v[114:115], v[142:143]
	v_pk_mul_f32 v[148:149], v[146:147], v[146:147]
	v_pk_mul_f32 v[114:115], v[118:119], v[140:141]
	v_pk_mul_f32 v[142:143], v[118:119], v[152:153]
	v_fma_f32 v156, v22, v114, 0
	v_add_f32_e32 v28, 0, v114
	v_add_f32_e32 v114, 0, v142
	v_fmac_f32_e32 v156, v23, v115
	v_add_f32_e32 v157, v115, v28
	v_add_f32_e32 v164, v143, v114
	v_lshlrev_b32_e32 v114, 16, v97
	v_and_b32_e32 v115, 0xffff0000, v97
	v_pk_add_f32 v[116:117], v[116:117], v[114:115] neg_lo:[0,1] neg_hi:[0,1]
	v_add_f32_e32 v28, v148, v149
	v_pk_fma_f32 v[114:115], v[4:5], v[116:117], v[114:115]
	v_and_b32_e32 v151, 0xffff0000, v103
	v_pk_mul_f32 v[116:117], v[16:17], v[114:115]
	v_pk_add_f32 v[154:155], v[150:151], -1.0 op_sel_hi:[1,0]
	v_pk_mul_f32 v[142:143], v[116:117], v[116:117]
	v_lshlrev_b32_e32 v160, 16, v94
	v_add_f32_e32 v28, v142, v28
	v_add_f32_e32 v28, v143, v28
	v_pk_fma_f32 v[142:143], v[20:21], v[154:155], 1.0 op_sel_hi:[1,1,0]
	v_and_b32_e32 v161, 0xffff0000, v94
	v_add_f32_dpp v28, v28, v28 row_ror:1 row_mask:0xf bank_mask:0xf bound_ctrl:1
	v_pk_mul_f32 v[142:143], v[142:143], v[114:115]
	v_pk_mul_f32 v[114:115], v[116:117], v[150:151]
	v_add_f32_dpp v28, v28, v28 row_ror:2 row_mask:0xf bank_mask:0xf bound_ctrl:1
	v_lshlrev_b32_e32 v162, 16, v95
	v_and_b32_e32 v163, 0xffff0000, v95
	v_add_f32_dpp v28, v28, v28 row_ror:4 row_mask:0xf bank_mask:0xf bound_ctrl:1
	v_pk_add_f32 v[108:109], v[108:109], v[160:161] neg_lo:[0,1] neg_hi:[0,1]
	v_pk_add_f32 v[110:111], v[110:111], v[162:163] neg_lo:[0,1] neg_hi:[0,1]
	v_add_f32_dpp v28, v28, v28 row_ror:8 row_mask:0xf bank_mask:0xf bound_ctrl:1
	v_max_f32_e32 v28, 0x179abe15, v28
	v_rsq_f32_e32 v28, v28
	v_pk_fma_f32 v[110:111], v[8:9], v[110:111], v[162:163]
	v_pk_fma_f32 v[108:109], v[6:7], v[108:109], v[160:161]
	v_pk_mul_f32 v[150:151], v[116:117], v[28:29] op_sel_hi:[1,0] neg_lo:[0,1] neg_hi:[0,1]
	v_lshlrev_b32_e32 v116, 16, v85
	v_and_b32_e32 v117, 0xffff0000, v85
	v_pk_add_f32 v[112:113], v[112:113], v[116:117] neg_lo:[0,1] neg_hi:[0,1]
	v_pk_mul_f32 v[154:155], v[114:115], v[28:29] op_sel_hi:[1,0]
	v_pk_fma_f32 v[158:159], v[12:13], v[112:113], v[116:117]
	v_pk_mul_f32 v[148:149], v[146:147], v[28:29] op_sel_hi:[1,0] neg_lo:[0,1] neg_hi:[0,1]
	v_pk_mul_f32 v[112:113], v[158:159], v[142:143]
	v_pk_mul_f32 v[114:115], v[158:159], v[114:115]
	v_fmac_f32_e32 v156, v24, v112
	v_add_f32_e32 v112, v112, v157
	v_add_f32_e32 v114, v114, v164
	v_cvt_f32_f16_sdwa v147, v99 dst_sel:DWORD dst_unused:UNUSED_PAD src0_sel:WORD_1
	v_cvt_f32_f16_e32 v146, v99
	v_fmac_f32_e32 v156, v25, v113
	v_add_f32_e32 v112, v113, v112
	v_add_f32_e32 v113, v115, v114
	v_add_f32_dpp v114, v156, v156 row_ror:1 row_mask:0xf bank_mask:0xf bound_ctrl:1
	v_add_f32_dpp v112, v112, v112 row_ror:1 row_mask:0xf bank_mask:0xf bound_ctrl:1
	v_add_f32_dpp v113, v113, v113 row_ror:1 row_mask:0xf bank_mask:0xf bound_ctrl:1
	v_add_f32_dpp v114, v114, v114 row_ror:2 row_mask:0xf bank_mask:0xf bound_ctrl:1
	v_add_f32_dpp v116, v112, v112 row_ror:2 row_mask:0xf bank_mask:0xf bound_ctrl:1
	v_add_f32_dpp v113, v113, v113 row_ror:2 row_mask:0xf bank_mask:0xf bound_ctrl:1
	v_add_f32_dpp v112, v114, v114 row_ror:4 row_mask:0xf bank_mask:0xf bound_ctrl:1
	v_add_f32_dpp v114, v116, v116 row_ror:4 row_mask:0xf bank_mask:0xf bound_ctrl:1
	v_add_f32_dpp v115, v113, v113 row_ror:4 row_mask:0xf bank_mask:0xf bound_ctrl:1
	v_mov_b32_e32 v116, 0
	v_mov_b32_e32 v117, 0
	v_mov_b32_e32 v113, 0
	v_pk_add_f32 v[146:147], v[146:147], 1.0 op_sel_hi:[1,0] neg_lo:[1,0] neg_hi:[1,0]
	v_mov_b32_dpp v116, v115 row_ror:8 row_mask:0xf bank_mask:0xf
	v_mov_b32_dpp v117, v114 row_ror:8 row_mask:0xf bank_mask:0xf
	v_mov_b32_dpp v113, v112 row_ror:8 row_mask:0xf bank_mask:0xf
	v_pk_mul_f32 v[152:153], v[152:153], v[28:29] op_sel_hi:[1,0]
	v_pk_mul_f32 v[156:157], v[118:119], 1.0 op_sel_hi:[1,0]
	v_pk_mul_f32 v[158:159], v[158:159], 1.0 op_sel_hi:[1,0]
	ds_write_b128 v129, v[108:111] offset:1280
	v_pk_mul_f32 v[196:197], v[174:175], v[144:145]
	v_pk_mul_f32 v[198:199], v[176:177], v[146:147]
	ds_bpermute_b32 v200, v233, v196
	ds_bpermute_b32 v201, v233, v197
	ds_bpermute_b32 v202, v233, v198
	ds_bpermute_b32 v203, v233, v199
	s_waitcnt lgkmcnt(0)
; #define LAS __attribute__((address_space(3)))
; __device__ __forceinline__ float scan_prepare(const ScanRegs& R, const u32x2 qr_, const u32x2 qk_, const u32x2 qv_, LAS float* slot, int cq, const f32x4 mur, const f32x4 muk, const f32x4 muv, const f32x4 kkc, const f32x4 kac, const f32x4 rkc) {
;     ...
;     f32x4 o_al, o_be, o_wr;
; #pragma unroll
;     for (int j = 0; j < 4; ++j) { o_al[j] = -(kn[j] * inv); o_be[j] = bu[j] * inv; o_wr[j] = dec[j] * rr[j]; }
;     LAS f32x4* s4 = (LAS f32x4*)slot;
;     s4[cq] = (f32x4){dec[0], dec[1], dec[2], dec[3]}; s4[16 + cq] = (f32x4){k2[0], k2[1], k2[2], k2[3]}; s4[32 + cq] = o_al; s4[48 + cq] = o_be; s4[64 + cq] = o_wr;
;     s4[80 + cq] = (f32x4){vv[0], vv[1], vv[2], vv[3]};
;     if (cq == 0) *(LAS f32x2*)(slot + 384) = (f32x2){c1 * inv, c2};
	v_fma_f32 v200, v200, v235, v236
	v_fma_f32 v201, v201, v235, v236
	v_fma_f32 v202, v202, v235, v236
	v_fma_f32 v203, v203, v235, v236
	v_pk_mul_f32 v[204:205], v[196:197], v[200:201]
	v_pk_mul_f32 v[206:207], v[198:199], v[202:203]
	ds_bpermute_b32 v208, v234, v204
	ds_bpermute_b32 v209, v234, v205
	ds_bpermute_b32 v210, v234, v206
	ds_bpermute_b32 v211, v234, v207
	s_waitcnt lgkmcnt(0)
	v_fma_f32 v208, v208, v237, v238
	v_fma_f32 v209, v209, v237, v238
	v_fma_f32 v210, v210, v237, v238
	v_fma_f32 v211, v211, v237, v238
	v_pk_mul_f32 v[212:213], v[200:201], v[208:209]
	v_pk_mul_f32 v[214:215], v[202:203], v[210:211]
	v_pk_mul_f32 v[216:217], v[212:213], v[174:175]
	v_pk_mul_f32 v[218:219], v[214:215], v[176:177]
	v_pk_mul_f32 v[220:221], v[216:217], v[144:145]
	v_pk_mul_f32 v[222:223], v[218:219], v[146:147]
	v_rcp_f32_e32 v224, v216
	v_rcp_f32_e32 v225, v217
	v_rcp_f32_e32 v226, v218
	v_rcp_f32_e32 v227, v219
	v_rcp_f32_e32 v228, v220
	v_rcp_f32_e32 v229, v221
	v_rcp_f32_e32 v230, v222
	v_rcp_f32_e32 v231, v223
	s_nop 0
	v_pk_mul_f32 v[182:183], v[182:183], v[212:213]
	v_pk_mul_f32 v[184:185], v[184:185], v[214:215]
	v_pk_mul_f32 v[178:179], v[178:179], v[224:225]
	v_pk_mul_f32 v[180:181], v[180:181], v[226:227]
	ds_write_b128 v194, v[178:181] offset:256
	s_nop 7
	s_nop 7
	v_pk_mul_f32 v[186:187], v[186:187], v[224:225]
	v_pk_mul_f32 v[188:189], v[188:189], v[226:227]
	ds_write_b128 v194, v[182:185] offset:512
	s_nop 7
	s_nop 7
	v_pk_mul_f32 v[190:191], v[190:191], v[216:217]
	v_pk_mul_f32 v[192:193], v[192:193], v[218:219]
	ds_write_b128 v194, v[186:189] offset:768
	s_nop 7
	s_nop 7
	v_pk_mul_f32 v[240:241], v[140:141], v[228:229]
	v_pk_mul_f32 v[242:243], v[142:143], v[230:231]
	ds_write_b128 v194, v[190:193] offset:1024
	s_nop 7
	s_nop 7
	v_pk_mul_f32 v[244:245], v[148:149], v[216:217]
	v_pk_mul_f32 v[246:247], v[150:151], v[218:219]
	ds_write_b128 v129, v[220:223]
	s_nop 7
	s_nop 7
	v_pk_mul_f32 v[196:197], v[152:153], v[228:229]
	v_pk_mul_f32 v[198:199], v[154:155], v[230:231]
	ds_write_b128 v129, v[240:243] offset:256
	s_nop 7
	s_nop 7
	v_pk_mul_f32 v[200:201], v[156:157], v[220:221]
	v_pk_mul_f32 v[202:203], v[158:159], v[222:223]
	ds_write_b128 v129, v[244:247] offset:512
	s_nop 7
	s_nop 7
	ds_write_b128 v129, v[196:199] offset:768
	s_nop 7
	s_nop 7
	ds_write_b128 v129, v[200:203] offset:1024
	s_nop 7
	s_nop 7
	s_and_saveexec_b64 s[56:57], s[4:5]
	s_cbranch_execz .LBB0_1123
	v_add_f32_e32 v108, v115, v116
	v_mul_f32_e32 v108, v108, v28
	v_add_f32_e32 v109, v114, v117
	ds_write_b64 v128, v[108:109] offset:1536
	s_or_b64 exec, exec, s[56:57]
	s_and_saveexec_b64 s[56:57], s[44:45]
	s_cbranch_execnz .LBB0_1124

; __global__ void __launch_bounds__(NTHR, 2) mega(Args a) {
;     extern __shared__ __attribute__((aligned(16))) unsigned char lds_raw[];
	.amdhsa_kernel _Z4mega4Args
		.amdhsa_group_segment_fixed_size 0
		.amdhsa_private_segment_fixed_size 0
		.amdhsa_kernarg_size 512
		.amdhsa_user_sgpr_count 2
		.amdhsa_user_sgpr_dispatch_ptr 0
		.amdhsa_user_sgpr_queue_ptr 0
		.amdhsa_user_sgpr_kernarg_segment_ptr 1
		.amdhsa_user_sgpr_dispatch_id 0
		.amdhsa_user_sgpr_kernarg_preload_length 0
		.amdhsa_user_sgpr_kernarg_preload_offset 0
		.amdhsa_user_sgpr_private_segment_size 0
		.amdhsa_uses_dynamic_stack 0
		.amdhsa_enable_private_segment 0
		.amdhsa_system_sgpr_workgroup_id_x 1
		.amdhsa_system_sgpr_workgroup_id_y 0
		.amdhsa_system_sgpr_workgroup_id_z 0
		.amdhsa_system_sgpr_workgroup_info 0
		.amdhsa_system_vgpr_workitem_id 2
		.amdhsa_next_free_vgpr 248
		.amdhsa_next_free_sgpr 102
		.amdhsa_accum_offset 248
		.amdhsa_reserve_vcc 1
		.amdhsa_float_round_mode_32 0
		.amdhsa_float_round_mode_16_64 0
		.amdhsa_float_denorm_mode_32 3
		.amdhsa_float_denorm_mode_16_64 3
		.amdhsa_dx10_clamp 1
		.amdhsa_ieee_mode 1
		.amdhsa_fp16_overflow 0
		.amdhsa_tg_split 0
		.amdhsa_exception_fp_ieee_invalid_op 0
		.amdhsa_exception_fp_denorm_src 0
		.amdhsa_exception_fp_ieee_div_zero 0
		.amdhsa_exception_fp_ieee_overflow 0
		.amdhsa_exception_fp_ieee_underflow 0
		.amdhsa_exception_fp_ieee_inexact 0
		.amdhsa_exception_int_div_zero 0
	.end_amdhsa_kernel

; __global__ void __launch_bounds__(NTHR, 2) mega(Args a) {
;     extern __shared__ __attribute__((aligned(16))) unsigned char lds_raw[];
amdhsa.kernels:
  - .agpr_count:     0
    .args:
      - .offset:         0
        .size:           256
        .value_kind:     by_value
      - .offset:         256
        .size:           4
        .value_kind:     hidden_block_count_x
      - .offset:         260
        .size:           4
        .value_kind:     hidden_block_count_y
      - .offset:         264
        .size:           4
        .value_kind:     hidden_block_count_z
      - .offset:         268
        .size:           2
        .value_kind:     hidden_group_size_x
      - .offset:         270
        .size:           2
        .value_kind:     hidden_group_size_y
      - .offset:         272
        .size:           2
        .value_kind:     hidden_group_size_z
      - .offset:         274
        .size:           2
        .value_kind:     hidden_remainder_x
      - .offset:         276
        .size:           2
        .value_kind:     hidden_remainder_y
      - .offset:         278
        .size:           2
        .value_kind:     hidden_remainder_z
      - .offset:         296
        .size:           8
        .value_kind:     hidden_global_offset_x
      - .offset:         304
        .size:           8
        .value_kind:     hidden_global_offset_y
      - .offset:         312
        .size:           8
        .value_kind:     hidden_global_offset_z
      - .offset:         320
        .size:           2
        .value_kind:     hidden_grid_dims
      - .offset:         344
        .size:           8
        .value_kind:     hidden_multigrid_sync_arg
      - .offset:         376
        .size:           4
        .value_kind:     hidden_dynamic_lds_size
    .group_segment_fixed_size: 0
    .kernarg_segment_align: 8
    .kernarg_segment_size: 512
    .language:       OpenCL C
    .language_version:
      - 2
      - 0
    .max_flat_workgroup_size: 512
    .name:           _Z4mega4Args
    .private_segment_fixed_size: 0
    .sgpr_count:     108
    .sgpr_spill_count: 86
    .symbol:         _Z4mega4Args.kd
    .uniform_work_group_size: 1
    .uses_dynamic_stack: false
    .vgpr_count:     248
    .vgpr_spill_count: 0
    .wavefront_size: 64
